# attn combine double-buffered (next trip's 24 loads in flight during this trip's math and stores), CAT stores plain again; scan SC loads hoisted to the top of the scanning block
# baseline (speedup 1.0000x reference)
; #define LAS __attribute__((address_space(3)))
; __device__ __forceinline__ void s5_scan_block(LAS unsigned char* lds, const Args& a, const float* __restrict__ SC, bf16* HP, int g, int wave, int lane) {
;     const int n = lane;
;     const float are = a.in[3][g * 64 + n], aim = a.in[4][g * 64 + n], dt = expf(a.in[5][g]);
;     const float eT = expf(are * dt * (float)ST), atr = eT * cosf(aim * dt * (float)ST), ati = eT * sinf(aim * dt * (float)ST);
;     const float eS = expf(are * dt * (float)(ST * 64)), asr = eS * cosf(aim * dt * (float)(ST * 64)), asi = eS * sinf(aim * dt * (float)(ST * 64));
;     const int c0 = wave * 64;
;     const float* sc = SC + ((size_t)g * SNC + c0) * 128; bf16* hp = HP + ((size_t)g * SNC + c0) * 128;
;     LAS float* ex = (LAS float*)lds;
;     float sr0[16], si0[16];
; __global__ void __launch_bounds__(512, 2) mega(Args a) {
;     ...
;     if (IN(3)) {
;         unsigned* flg = (unsigned*)(ws + WS_CNT) + 64 * 64;
;         const int G = (int)gridDim.x, b = (int)blockIdx.x;
;         if (G == 256) {
;             if (b < NG) {
;                 s5_scan_block(lds, a, SC, HP, b, wave, lane);
.LBB0_751:
	s_and_b64 vcc, exec, s[0:1]
	s_cbranch_vccz .LBB0_811
	s_add_u32 s24, s88, 0x904000
	s_addc_u32 s25, s89, 0
	s_and_b64 vcc, exec, s[4:5]
	s_cbranch_vccnz .LBB0_782
	v_readlane_b32 s26, v245, 1
	s_and_b32 s26, s26, 0xffffffc0
	s_lshl_b32 s26, s26, 9
	s_lshl_b32 s27, s66, 18
	s_add_i32 s26, s26, s27
	v_lshl_add_u32 v195, v184, 2, s26
	s_add_u32 s26, s88, 0x18c00000
	s_addc_u32 s27, s89, 0
	global_load_dword v64, v195, s[26:27]
	global_load_dword v65, v195, s[26:27] offset:256
	global_load_dword v66, v195, s[26:27] offset:512
	global_load_dword v67, v195, s[26:27] offset:768
	global_load_dword v68, v195, s[26:27] offset:1024
	global_load_dword v69, v195, s[26:27] offset:1280
	global_load_dword v70, v195, s[26:27] offset:1536
	global_load_dword v71, v195, s[26:27] offset:1792
	global_load_dword v72, v195, s[26:27] offset:2048
	global_load_dword v73, v195, s[26:27] offset:2304
	global_load_dword v74, v195, s[26:27] offset:2560
	global_load_dword v75, v195, s[26:27] offset:2816
	global_load_dword v76, v195, s[26:27] offset:3072
	global_load_dword v77, v195, s[26:27] offset:3328
	global_load_dword v78, v195, s[26:27] offset:3584
	global_load_dword v79, v195, s[26:27] offset:3840
	v_add_u32_e32 v195, 0x1000, v195
	global_load_dword v80, v195, s[26:27]
	global_load_dword v81, v195, s[26:27] offset:256
	global_load_dword v82, v195, s[26:27] offset:512
	global_load_dword v83, v195, s[26:27] offset:768
	global_load_dword v84, v195, s[26:27] offset:1024
	global_load_dword v85, v195, s[26:27] offset:1280
	global_load_dword v86, v195, s[26:27] offset:1536
	global_load_dword v87, v195, s[26:27] offset:1792
	global_load_dword v88, v195, s[26:27] offset:2048
	global_load_dword v89, v195, s[26:27] offset:2304
	global_load_dword v90, v195, s[26:27] offset:2560
	global_load_dword v91, v195, s[26:27] offset:2816
	global_load_dword v92, v195, s[26:27] offset:3072
	global_load_dword v93, v195, s[26:27] offset:3328
	global_load_dword v94, v195, s[26:27] offset:3584
	global_load_dword v95, v195, s[26:27] offset:3840
	v_add_u32_e32 v195, 0x1000, v195
	global_load_dword v96, v195, s[26:27]
	global_load_dword v97, v195, s[26:27] offset:256
	global_load_dword v98, v195, s[26:27] offset:512
	global_load_dword v99, v195, s[26:27] offset:768
	global_load_dword v100, v195, s[26:27] offset:1024
	global_load_dword v101, v195, s[26:27] offset:1280
	global_load_dword v102, v195, s[26:27] offset:1536
	global_load_dword v103, v195, s[26:27] offset:1792
	global_load_dword v104, v195, s[26:27] offset:2048
	global_load_dword v105, v195, s[26:27] offset:2304
	global_load_dword v106, v195, s[26:27] offset:2560
	global_load_dword v107, v195, s[26:27] offset:2816
	global_load_dword v108, v195, s[26:27] offset:3072
	global_load_dword v109, v195, s[26:27] offset:3328
	global_load_dword v110, v195, s[26:27] offset:3584
	global_load_dword v111, v195, s[26:27] offset:3840
	v_add_u32_e32 v195, 0x1000, v195
	global_load_dword v112, v195, s[26:27]
	global_load_dword v113, v195, s[26:27] offset:256
	global_load_dword v114, v195, s[26:27] offset:512
	global_load_dword v115, v195, s[26:27] offset:768
	global_load_dword v116, v195, s[26:27] offset:1024
	global_load_dword v117, v195, s[26:27] offset:1280
	global_load_dword v118, v195, s[26:27] offset:1536
	global_load_dword v119, v195, s[26:27] offset:1792
	global_load_dword v120, v195, s[26:27] offset:2048
	global_load_dword v121, v195, s[26:27] offset:2304
	global_load_dword v122, v195, s[26:27] offset:2560
	global_load_dword v123, v195, s[26:27] offset:2816
	global_load_dword v124, v195, s[26:27] offset:3072
	global_load_dword v125, v195, s[26:27] offset:3328
	global_load_dword v126, v195, s[26:27] offset:3584
	global_load_dword v127, v195, s[26:27] offset:3840
	v_add_u32_e32 v195, 0x1000, v195
	global_load_dword v128, v195, s[26:27]
	global_load_dword v129, v195, s[26:27] offset:256
	global_load_dword v130, v195, s[26:27] offset:512
	global_load_dword v131, v195, s[26:27] offset:768
	global_load_dword v132, v195, s[26:27] offset:1024
	global_load_dword v133, v195, s[26:27] offset:1280
	global_load_dword v134, v195, s[26:27] offset:1536
	global_load_dword v135, v195, s[26:27] offset:1792
	global_load_dword v136, v195, s[26:27] offset:2048
	global_load_dword v137, v195, s[26:27] offset:2304
	global_load_dword v138, v195, s[26:27] offset:2560
	global_load_dword v139, v195, s[26:27] offset:2816
	global_load_dword v140, v195, s[26:27] offset:3072
	global_load_dword v141, v195, s[26:27] offset:3328
	global_load_dword v142, v195, s[26:27] offset:3584
	global_load_dword v143, v195, s[26:27] offset:3840
	v_add_u32_e32 v195, 0x1000, v195
	global_load_dword v144, v195, s[26:27]
	global_load_dword v145, v195, s[26:27] offset:256
	global_load_dword v146, v195, s[26:27] offset:512
	global_load_dword v147, v195, s[26:27] offset:768
	global_load_dword v148, v195, s[26:27] offset:1024
	global_load_dword v149, v195, s[26:27] offset:1280
	global_load_dword v150, v195, s[26:27] offset:1536
	global_load_dword v151, v195, s[26:27] offset:1792
	global_load_dword v152, v195, s[26:27] offset:2048
	global_load_dword v153, v195, s[26:27] offset:2304
	global_load_dword v154, v195, s[26:27] offset:2560
	global_load_dword v155, v195, s[26:27] offset:2816
	global_load_dword v156, v195, s[26:27] offset:3072
	global_load_dword v157, v195, s[26:27] offset:3328
	global_load_dword v158, v195, s[26:27] offset:3584
	global_load_dword v159, v195, s[26:27] offset:3840
	v_add_u32_e32 v195, 0x1000, v195
	global_load_dword v160, v195, s[26:27]
	global_load_dword v161, v195, s[26:27] offset:256
	global_load_dword v162, v195, s[26:27] offset:512
	global_load_dword v163, v195, s[26:27] offset:768
; #define LAS __attribute__((address_space(3)))
; __device__ __forceinline__ void s5_scan_block(LAS unsigned char* lds, const Args& a, const float* __restrict__ SC, bf16* HP, int g, int wave, int lane) {
;     ...
;     const float are = a.in[3][g * 64 + n], aim = a.in[4][g * 64 + n], dt = expf(a.in[5][g]);
;     const float eT = expf(are * dt * (float)ST), atr = eT * cosf(aim * dt * (float)ST), ati = eT * sinf(aim * dt * (float)ST);
;     const float eS = expf(are * dt * (float)(ST * 64)), asr = eS * cosf(aim * dt * (float)(ST * 64)), asi = eS * sinf(aim * dt * (float)(ST * 64));
;     const int c0 = wave * 64;
;     const float* sc = SC + ((size_t)g * SNC + c0) * 128; bf16* hp = HP + ((size_t)g * SNC + c0) * 128;
;     LAS float* ex = (LAS float*)lds;
;     float sr0[16], si0[16];
	global_load_dword v164, v195, s[26:27] offset:1024
	global_load_dword v165, v195, s[26:27] offset:1280
	global_load_dword v166, v195, s[26:27] offset:1536
	global_load_dword v167, v195, s[26:27] offset:1792
	global_load_dword v168, v195, s[26:27] offset:2048
	global_load_dword v169, v195, s[26:27] offset:2304
	global_load_dword v170, v195, s[26:27] offset:2560
	global_load_dword v171, v195, s[26:27] offset:2816
	global_load_dword v172, v195, s[26:27] offset:3072
	global_load_dword v173, v195, s[26:27] offset:3328
	global_load_dword v174, v195, s[26:27] offset:3584
	global_load_dword v175, v195, s[26:27] offset:3840
	v_add_u32_e32 v195, 0x1000, v195
	global_load_dword v176, v195, s[26:27]
	global_load_dword v177, v195, s[26:27] offset:256
	global_load_dword v178, v195, s[26:27] offset:512
	global_load_dword v179, v195, s[26:27] offset:768
	global_load_dword v180, v195, s[26:27] offset:1024
	global_load_dword v181, v195, s[26:27] offset:1280
	global_load_dword v182, v195, s[26:27] offset:1536
	global_load_dword v183, v195, s[26:27] offset:1792
	global_load_dword v196, v195, s[26:27] offset:2048
	global_load_dword v197, v195, s[26:27] offset:2304
	global_load_dword v198, v195, s[26:27] offset:2560
	global_load_dword v199, v195, s[26:27] offset:2816
	global_load_dword v200, v195, s[26:27] offset:3072
	global_load_dword v201, v195, s[26:27] offset:3328
	global_load_dword v202, v195, s[26:27] offset:3584
	global_load_dword v203, v195, s[26:27] offset:3840
	s_ashr_i32 s67, s66, 31
	s_lshl_b32 s8, s66, 6
	s_lshl_b64 s[0:1], s[66:67], 2
	s_add_u32 s0, s22, s0
	s_addc_u32 s1, s23, s1
	v_mov_b32_e32 v1, 0
	global_load_dword v0, v1, s[0:1]
	v_or_b32_e32 v2, s8, v184
	v_ashrrev_i32_e32 v3, 31, v2
	v_lshlrev_b64 v[2:3], 2, v[2:3]
	v_lshl_add_u64 v[4:5], s[20:21], 0, v[2:3]
	global_load_dword v6, v[4:5], off
	v_lshl_add_u64 v[2:3], s[18:19], 0, v[2:3]
	global_load_dword v4, v[2:3], off
	s_mov_b32 s0, 0x3fb8aa3b
	s_mov_b32 s1, 0xc2ce8ed0
	s_brev_b32 s2, 18
	s_waitcnt vmcnt(2)
	v_mul_f32_e32 v2, 0x3fb8aa3b, v0
	v_fma_f32 v3, v0, s0, -v2
	v_rndne_f32_e32 v5, v2
	v_fmamk_f32 v3, v0, 0x32a5705f, v3
	v_sub_f32_e32 v2, v2, v5
	v_add_f32_e32 v2, v2, v3
	v_cvt_i32_f32_e32 v5, v5
	v_exp_f32_e32 v2, v2
	s_mov_b32 s0, 0x42b17218
	v_cmp_ngt_f32_e32 vcc, s1, v0
	v_mov_b32_e32 v3, 0x7f800000
	v_ldexp_f32 v2, v2, v5
	v_cndmask_b32_e32 v2, 0, v2, vcc
	v_cmp_nlt_f32_e32 vcc, s0, v0
	s_nop 1
	v_cndmask_b32_e32 v5, v3, v2, vcc
	s_waitcnt vmcnt(1)
	v_mul_f32_e32 v3, v6, v5
	v_mul_f32_e32 v2, 0x42000000, v3
	v_and_b32_e32 v6, 0x7fffffff, v2
	v_cmp_nlt_f32_e64 s[18:19], |v2|, s2
	v_lshrrev_b32_e32 v10, 23, v6
	s_and_saveexec_b64 s[0:1], s[18:19]
	s_xor_b64 s[20:21], exec, s[0:1]
	s_cbranch_execz .LBB0_755
	v_add_u32_e32 v0, 0xffffff88, v10
	v_not_b32_e32 v7, 63
	v_cmp_lt_u32_e32 vcc, 63, v0
	s_mov_b32 s2, 0xfe5163ab
	s_nop 0
	v_cndmask_b32_e32 v7, 0, v7, vcc
	v_add_u32_e32 v0, v7, v0
	v_not_b32_e32 v7, 31
	v_cmp_lt_u32_e64 s[0:1], 31, v0
	s_nop 1
	v_cndmask_b32_e64 v8, 0, v7, s[0:1]
	v_add_u32_e32 v0, v8, v0
	v_cmp_lt_u32_e64 s[4:5], 31, v0
	s_nop 1
	v_cndmask_b32_e64 v7, 0, v7, s[4:5]
	v_add_u32_e32 v7, v7, v0
	v_and_b32_e32 v0, 0x7fffff, v6
	v_or_b32_e32 v11, 0x800000, v0
	v_mad_u64_u32 v[8:9], s[2:3], v11, s2, 0
	v_mov_b32_e32 v0, v9
	s_mov_b32 s2, 0x3c439041
	v_mad_u64_u32 v[12:13], s[2:3], v11, s2, v[0:1]
	v_mov_b32_e32 v0, v13
	s_mov_b32 s2, 0xdb629599
	v_mad_u64_u32 v[14:15], s[2:3], v11, s2, v[0:1]
	v_mov_b32_e32 v0, v15
	s_mov_b32 s2, 0xf534ddc0
	v_mad_u64_u32 v[16:17], s[2:3], v11, s2, v[0:1]
	v_mov_b32_e32 v0, v17
	s_mov_b32 s2, 0xfc2757d1
	v_mad_u64_u32 v[18:19], s[2:3], v11, s2, v[0:1]
	v_mov_b32_e32 v0, v19
	s_mov_b32 s2, 0x4e441529
	v_mad_u64_u32 v[20:21], s[2:3], v11, s2, v[0:1]
	v_mov_b32_e32 v0, v21
	s_mov_b32 s2, 0xa2f9836e
	v_mad_u64_u32 v[0:1], s[2:3], v11, s2, v[0:1]
	v_cndmask_b32_e32 v9, v20, v16, vcc
	v_cndmask_b32_e32 v0, v0, v18, vcc
	v_cndmask_b32_e32 v1, v1, v20, vcc
	v_cndmask_b32_e64 v11, v0, v9, s[0:1]
	v_cndmask_b32_e64 v0, v1, v0, s[0:1]
	v_cndmask_b32_e32 v1, v18, v14, vcc
	v_cndmask_b32_e64 v9, v9, v1, s[0:1]
	v_sub_u32_e32 v13, 32, v7
	v_cmp_eq_u32_e64 s[6:7], 0, v7
	v_cndmask_b32_e32 v7, v16, v12, vcc
	v_cndmask_b32_e64 v0, v0, v11, s[4:5]
	v_cndmask_b32_e64 v11, v11, v9, s[4:5]
	v_cndmask_b32_e64 v1, v1, v7, s[0:1]
	v_alignbit_b32 v15, v0, v11, v13
	v_cndmask_b32_e64 v9, v9, v1, s[4:5]
	v_cndmask_b32_e64 v0, v15, v0, s[6:7]
	v_alignbit_b32 v12, v11, v9, v13
	v_cndmask_b32_e32 v8, v14, v8, vcc
	v_cndmask_b32_e64 v11, v12, v11, s[6:7]
	v_bfe_u32 v16, v0, 29, 1
	v_cndmask_b32_e64 v7, v7, v8, s[0:1]
	v_alignbit_b32 v12, v0, v11, 30
	v_sub_u32_e32 v17, 0, v16
	v_cndmask_b32_e64 v1, v1, v7, s[4:5]
	v_xor_b32_e32 v12, v12, v17
	v_alignbit_b32 v7, v9, v1, v13
	v_cndmask_b32_e64 v7, v7, v9, s[6:7]
	v_ffbh_u32_e32 v9, v12
	v_alignbit_b32 v8, v11, v7, 30
	v_min_u32_e32 v9, 32, v9
	v_alignbit_b32 v1, v7, v1, 30
	v_xor_b32_e32 v8, v8, v17
	v_sub_u32_e32 v11, 31, v9
	v_xor_b32_e32 v1, v1, v17
	v_alignbit_b32 v12, v12, v8, v11
	v_alignbit_b32 v1, v8, v1, v11
	v_alignbit_b32 v7, v12, v1, 9
	v_ffbh_u32_e32 v8, v7
	v_min_u32_e32 v8, 32, v8
	v_lshrrev_b32_e32 v15, 29, v0
	v_not_b32_e32 v11, v8
	v_alignbit_b32 v1, v7, v1, v11
	v_lshlrev_b32_e32 v7, 31, v15
	v_or_b32_e32 v11, 0x33000000, v7
	v_add_lshl_u32 v8, v8, v9, 23
	v_lshrrev_b32_e32 v1, 9, v1
	v_sub_u32_e32 v8, v11, v8
	v_or_b32_e32 v7, 0.5, v7
	v_lshlrev_b32_e32 v9, 23, v9
	v_or_b32_e32 v1, v8, v1
	v_lshrrev_b32_e32 v8, 9, v12
	v_sub_u32_e32 v7, v7, v9
	v_or_b32_e32 v7, v8, v7
	s_mov_b32 s0, 0x3fc90fda
	v_mul_f32_e32 v8, 0x3fc90fda, v7
	v_fma_f32 v9, v7, s0, -v8
	v_fmamk_f32 v7, v7, 0x33a22168, v9
	v_fmac_f32_e32 v7, 0x3fc90fda, v1
	v_lshrrev_b32_e32 v0, 30, v0
	v_add_f32_e32 v8, v8, v7
	v_add_u32_e32 v7, v16, v0

; #define LBAR() do { asm volatile("s_waitcnt lgkmcnt(0)" ::: "memory"); __builtin_amdgcn_s_barrier(); asm volatile("" ::: "memory"); } while (0)
; #define S5_LOAD(SR, SI, cb) do { _Pragma("unroll") for (int i = 0; i < 16; ++i) { SR[i] = sc[(size_t)((cb) + i) * 128 + n]; SI[i] = sc[(size_t)((cb) + i) * 128 + 64 + n]; } } while (0)
; #define S5_ACC(SR, SI) do { _Pragma("unroll") for (int i = 0; i < 16; ++i) { const float nhr = atr * hr - ati * hi + SR[i], nhi = atr * hi + ati * hr + SI[i]; hr = nhr; hi = nhi; } } while (0)
; #define S5_STEP(SR, SI, cb) do { _Pragma("unroll") for (int i = 0; i < 16; ++i) { \
;         hp[(size_t)((cb) + i) * 128 + n] = (bf16)f2bf(hr); hp[(size_t)((cb) + i) * 128 + 64 + n] = (bf16)f2bf(hi); \
;         const float nhr = atr * hr - ati * hi + SR[i], nhi = atr * hi + ati * hr + SI[i]; hr = nhr; hi = nhi; } } while (0)
; __device__ __forceinline__ void s5_scan_block(LAS unsigned char* lds, const Args& a, const float* __restrict__ SC, bf16* HP, int g, int wave, int lane) {
;     ...
;     float hr = 0.f, hi = 0.f;
;     for (int cb = 0; cb < 64; cb += 16) { S5_LOAD(sr0, si0, cb); S5_ACC(sr0, si0); }
;     LBAR();
;     ex[wave * 128 + n] = hr; ex[wave * 128 + 64 + n] = hi;
;     LBAR();
;     hr = 0.f; hi = 0.f;
;     for (int w = 0; w < wave; ++w) { const float er = ex[w * 128 + n], ei = ex[w * 128 + 64 + n]; const float nhr = asr * hr - asi * hi + er, nhi = asr * hi + asi * hr + ei; hr = nhr; hi = nhi; }
;     for (int cb = 0; cb < 64; cb += 16) { S5_LOAD(sr0, si0, cb); S5_STEP(sr0, si0, cb); }
.LBB0_777:
	s_lshl_b64 s[0:1], s[66:67], 17
	s_lshl_b64 s[2:3], s[4:5], 8
	s_add_u32 s0, s0, s2
	s_addc_u32 s1, s1, s3
	v_lshl_or_b32 v10, v184, 1, s0
	v_mov_b32_e32 v11, s1
	s_mov_b64 s[0:1], 0x19c00800
	v_lshl_add_u64 v[10:11], v[10:11], 0, s[0:1]
	s_lshl_b64 s[0:1], s[66:67], 18
	s_lshl_b64 s[2:3], s[4:5], 9
	s_add_u32 s0, s0, s2
	s_addc_u32 s1, s1, s3
	v_mov_b32_e32 v3, v2
	v_mov_b32_e32 v1, v0
	v_mov_b32_e32 v6, v2
	v_mov_b32_e32 v7, v0
	v_mov_b32_e32 v8, v0
	v_mov_b32_e32 v9, v2
	v_lshl_or_b32 v12, v184, 2, s0
	v_mov_b32_e32 v13, s1
	s_movk_i32 s9, 0x7fff
	s_mov_b64 s[2:3], 0x1000
	v_lshl_add_u64 v[14:15], s[88:89], 0, v[10:11]
	s_waitcnt vmcnt(0)
	v_bfe_u32 v20, v4, 16, 1
	v_bfe_u32 v21, v5, 16, 1
	v_mul_f32_e32 v22, v0, v5
	v_mul_f32_e32 v23, v0, v4
	v_add3_u32 v20, v4, v20, s9
	v_add3_u32 v21, v5, v21, s9
	v_fma_f32 v22, v2, v4, -v22
	v_fma_f32 v23, v2, v5, v23
	global_store_short_d16_hi v[14:15], v20, off offset:-2048
	global_store_short_d16_hi v[14:15], v21, off offset:-1920
	v_add_f32_e32 v4, v22, v64
	v_add_f32_e32 v5, v23, v65
	v_bfe_u32 v24, v4, 16, 1
	v_bfe_u32 v25, v5, 16, 1
	v_mul_f32_e32 v26, v0, v5
	v_mul_f32_e32 v27, v0, v4
	v_add3_u32 v24, v4, v24, s9
	v_add3_u32 v25, v5, v25, s9
	v_fma_f32 v26, v2, v4, -v26
	v_fma_f32 v27, v2, v5, v27
	global_store_short_d16_hi v[14:15], v24, off offset:-1792
	global_store_short_d16_hi v[14:15], v25, off offset:-1664
	v_add_f32_e32 v4, v26, v66
	v_add_f32_e32 v5, v27, v67
	v_bfe_u32 v20, v4, 16, 1
	v_bfe_u32 v21, v5, 16, 1
	v_mul_f32_e32 v22, v0, v5
	v_mul_f32_e32 v23, v0, v4
	v_add3_u32 v20, v4, v20, s9
	v_add3_u32 v21, v5, v21, s9
	v_fma_f32 v22, v2, v4, -v22
	v_fma_f32 v23, v2, v5, v23
	global_store_short_d16_hi v[14:15], v20, off offset:-1536
	global_store_short_d16_hi v[14:15], v21, off offset:-1408
	v_add_f32_e32 v4, v22, v68
	v_add_f32_e32 v5, v23, v69
	v_bfe_u32 v24, v4, 16, 1
	v_bfe_u32 v25, v5, 16, 1
	v_mul_f32_e32 v26, v0, v5
	v_mul_f32_e32 v27, v0, v4
	v_add3_u32 v24, v4, v24, s9
	v_add3_u32 v25, v5, v25, s9
	v_fma_f32 v26, v2, v4, -v26
	v_fma_f32 v27, v2, v5, v27
	global_store_short_d16_hi v[14:15], v24, off offset:-1280
	global_store_short_d16_hi v[14:15], v25, off offset:-1152
	v_add_f32_e32 v4, v26, v70
	v_add_f32_e32 v5, v27, v71
	v_bfe_u32 v20, v4, 16, 1
	v_bfe_u32 v21, v5, 16, 1
	v_mul_f32_e32 v22, v0, v5
	v_mul_f32_e32 v23, v0, v4
	v_add3_u32 v20, v4, v20, s9
	v_add3_u32 v21, v5, v21, s9
	v_fma_f32 v22, v2, v4, -v22
	v_fma_f32 v23, v2, v5, v23
	global_store_short_d16_hi v[14:15], v20, off offset:-1024
	global_store_short_d16_hi v[14:15], v21, off offset:-896
	v_add_f32_e32 v4, v22, v72
	v_add_f32_e32 v5, v23, v73
	v_bfe_u32 v24, v4, 16, 1
	v_bfe_u32 v25, v5, 16, 1
	v_mul_f32_e32 v26, v0, v5
	v_mul_f32_e32 v27, v0, v4
	v_add3_u32 v24, v4, v24, s9
	v_add3_u32 v25, v5, v25, s9
	v_fma_f32 v26, v2, v4, -v26
	v_fma_f32 v27, v2, v5, v27
	global_store_short_d16_hi v[14:15], v24, off offset:-768
	global_store_short_d16_hi v[14:15], v25, off offset:-640
	v_add_f32_e32 v4, v26, v74
	v_add_f32_e32 v5, v27, v75
	v_bfe_u32 v20, v4, 16, 1
	v_bfe_u32 v21, v5, 16, 1
	v_mul_f32_e32 v22, v0, v5
	v_mul_f32_e32 v23, v0, v4
	v_add3_u32 v20, v4, v20, s9
	v_add3_u32 v21, v5, v21, s9
	v_fma_f32 v22, v2, v4, -v22
	v_fma_f32 v23, v2, v5, v23
	global_store_short_d16_hi v[14:15], v20, off offset:-512
	global_store_short_d16_hi v[14:15], v21, off offset:-384
	v_add_f32_e32 v4, v22, v76
	v_add_f32_e32 v5, v23, v77
	v_bfe_u32 v24, v4, 16, 1
	v_bfe_u32 v25, v5, 16, 1
	v_mul_f32_e32 v26, v0, v5
	v_mul_f32_e32 v27, v0, v4
	v_add3_u32 v24, v4, v24, s9
	v_add3_u32 v25, v5, v25, s9
	v_fma_f32 v26, v2, v4, -v26
	v_fma_f32 v27, v2, v5, v27
	global_store_short_d16_hi v[14:15], v24, off offset:-256
	global_store_short_d16_hi v[14:15], v25, off offset:-128
	v_add_f32_e32 v4, v26, v78
	v_add_f32_e32 v5, v27, v79
	v_bfe_u32 v20, v4, 16, 1
	v_bfe_u32 v21, v5, 16, 1
	v_mul_f32_e32 v22, v0, v5
	v_mul_f32_e32 v23, v0, v4
	v_add3_u32 v20, v4, v20, s9
	v_add3_u32 v21, v5, v21, s9
	v_fma_f32 v22, v2, v4, -v22
	v_fma_f32 v23, v2, v5, v23
	global_store_short_d16_hi v[14:15], v20, off
	global_store_short_d16_hi v[14:15], v21, off offset:128
	v_add_f32_e32 v4, v22, v80
	v_add_f32_e32 v5, v23, v81
	v_bfe_u32 v24, v4, 16, 1
	v_bfe_u32 v25, v5, 16, 1
	v_mul_f32_e32 v26, v0, v5
	v_mul_f32_e32 v27, v0, v4
	v_add3_u32 v24, v4, v24, s9
	v_add3_u32 v25, v5, v25, s9
	v_fma_f32 v26, v2, v4, -v26
	v_fma_f32 v27, v2, v5, v27
	global_store_short_d16_hi v[14:15], v24, off offset:256
	global_store_short_d16_hi v[14:15], v25, off offset:384
	v_add_f32_e32 v4, v26, v82
	v_add_f32_e32 v5, v27, v83
	v_bfe_u32 v20, v4, 16, 1
	v_bfe_u32 v21, v5, 16, 1
	v_mul_f32_e32 v22, v0, v5
	v_mul_f32_e32 v23, v0, v4
	v_add3_u32 v20, v4, v20, s9
	v_add3_u32 v21, v5, v21, s9
	v_fma_f32 v22, v2, v4, -v22
	v_fma_f32 v23, v2, v5, v23
	global_store_short_d16_hi v[14:15], v20, off offset:512
	global_store_short_d16_hi v[14:15], v21, off offset:640
	v_add_f32_e32 v4, v22, v84
	v_add_f32_e32 v5, v23, v85
	v_bfe_u32 v24, v4, 16, 1
	v_bfe_u32 v25, v5, 16, 1
	v_mul_f32_e32 v26, v0, v5
	v_mul_f32_e32 v27, v0, v4
	v_add3_u32 v24, v4, v24, s9
	v_add3_u32 v25, v5, v25, s9
	v_fma_f32 v26, v2, v4, -v26
	v_fma_f32 v27, v2, v5, v27
	global_store_short_d16_hi v[14:15], v24, off offset:768
	global_store_short_d16_hi v[14:15], v25, off offset:896
	v_add_f32_e32 v4, v26, v86
	v_add_f32_e32 v5, v27, v87
	v_bfe_u32 v20, v4, 16, 1
	v_bfe_u32 v21, v5, 16, 1
	v_mul_f32_e32 v22, v0, v5
	v_mul_f32_e32 v23, v0, v4
	v_add3_u32 v20, v4, v20, s9
	v_add3_u32 v21, v5, v21, s9
	v_fma_f32 v22, v2, v4, -v22
	v_fma_f32 v23, v2, v5, v23
	global_store_short_d16_hi v[14:15], v20, off offset:1024
; #define LBAR() do { asm volatile("s_waitcnt lgkmcnt(0)" ::: "memory"); __builtin_amdgcn_s_barrier(); asm volatile("" ::: "memory"); } while (0)
; #define S5_LOAD(SR, SI, cb) do { _Pragma("unroll") for (int i = 0; i < 16; ++i) { SR[i] = sc[(size_t)((cb) + i) * 128 + n]; SI[i] = sc[(size_t)((cb) + i) * 128 + 64 + n]; } } while (0)
; #define S5_ACC(SR, SI) do { _Pragma("unroll") for (int i = 0; i < 16; ++i) { const float nhr = atr * hr - ati * hi + SR[i], nhi = atr * hi + ati * hr + SI[i]; hr = nhr; hi = nhi; } } while (0)
; #define S5_STEP(SR, SI, cb) do { _Pragma("unroll") for (int i = 0; i < 16; ++i) { \
;         hp[(size_t)((cb) + i) * 128 + n] = (bf16)f2bf(hr); hp[(size_t)((cb) + i) * 128 + 64 + n] = (bf16)f2bf(hi); \
;         const float nhr = atr * hr - ati * hi + SR[i], nhi = atr * hi + ati * hr + SI[i]; hr = nhr; hi = nhi; } } while (0)
; __device__ __forceinline__ void s5_scan_block(LAS unsigned char* lds, const Args& a, const float* __restrict__ SC, bf16* HP, int g, int wave, int lane) {
;     ...
;     float hr = 0.f, hi = 0.f;
;     for (int cb = 0; cb < 64; cb += 16) { S5_LOAD(sr0, si0, cb); S5_ACC(sr0, si0); }
;     LBAR();
;     ex[wave * 128 + n] = hr; ex[wave * 128 + 64 + n] = hi;
;     LBAR();
;     hr = 0.f; hi = 0.f;
;     for (int w = 0; w < wave; ++w) { const float er = ex[w * 128 + n], ei = ex[w * 128 + 64 + n]; const float nhr = asr * hr - asi * hi + er, nhi = asr * hi + asi * hr + ei; hr = nhr; hi = nhi; }
;     for (int cb = 0; cb < 64; cb += 16) { S5_LOAD(sr0, si0, cb); S5_STEP(sr0, si0, cb); }
	global_store_short_d16_hi v[14:15], v21, off offset:1152
	v_add_f32_e32 v4, v22, v88
	v_add_f32_e32 v5, v23, v89
	v_bfe_u32 v24, v4, 16, 1
	v_bfe_u32 v25, v5, 16, 1
	v_mul_f32_e32 v26, v0, v5
	v_mul_f32_e32 v27, v0, v4
	v_add3_u32 v24, v4, v24, s9
	v_add3_u32 v25, v5, v25, s9
	v_fma_f32 v26, v2, v4, -v26
	v_fma_f32 v27, v2, v5, v27
	global_store_short_d16_hi v[14:15], v24, off offset:1280
	global_store_short_d16_hi v[14:15], v25, off offset:1408
	v_add_f32_e32 v4, v26, v90
	v_add_f32_e32 v5, v27, v91
	v_bfe_u32 v20, v4, 16, 1
	v_bfe_u32 v21, v5, 16, 1
	v_mul_f32_e32 v22, v0, v5
	v_mul_f32_e32 v23, v0, v4
	v_add3_u32 v20, v4, v20, s9
	v_add3_u32 v21, v5, v21, s9
	v_fma_f32 v22, v2, v4, -v22
	v_fma_f32 v23, v2, v5, v23
	global_store_short_d16_hi v[14:15], v20, off offset:1536
	global_store_short_d16_hi v[14:15], v21, off offset:1664
	v_add_f32_e32 v4, v22, v92
	v_add_f32_e32 v5, v23, v93
	v_bfe_u32 v24, v4, 16, 1
	v_bfe_u32 v25, v5, 16, 1
	v_mul_f32_e32 v26, v0, v5
	v_mul_f32_e32 v27, v0, v4
	v_add3_u32 v24, v4, v24, s9
	v_add3_u32 v25, v5, v25, s9
	v_fma_f32 v26, v2, v4, -v26
	v_fma_f32 v27, v2, v5, v27
	global_store_short_d16_hi v[14:15], v24, off offset:1792
	global_store_short_d16_hi v[14:15], v25, off offset:1920
	v_add_f32_e32 v4, v26, v94
	v_add_f32_e32 v5, v27, v95
	v_lshl_add_u64 v[14:15], v[14:15], 0, s[2:3]
	v_bfe_u32 v20, v4, 16, 1
	v_bfe_u32 v21, v5, 16, 1
	v_mul_f32_e32 v22, v0, v5
	v_mul_f32_e32 v23, v0, v4
	v_add3_u32 v20, v4, v20, s9
	v_add3_u32 v21, v5, v21, s9
	v_fma_f32 v22, v2, v4, -v22
	v_fma_f32 v23, v2, v5, v23
	global_store_short_d16_hi v[14:15], v20, off offset:-2048
	global_store_short_d16_hi v[14:15], v21, off offset:-1920
	v_add_f32_e32 v4, v22, v96
	v_add_f32_e32 v5, v23, v97
	v_bfe_u32 v24, v4, 16, 1
	v_bfe_u32 v25, v5, 16, 1
	v_mul_f32_e32 v26, v0, v5
	v_mul_f32_e32 v27, v0, v4
	v_add3_u32 v24, v4, v24, s9
	v_add3_u32 v25, v5, v25, s9
	v_fma_f32 v26, v2, v4, -v26
	v_fma_f32 v27, v2, v5, v27
	global_store_short_d16_hi v[14:15], v24, off offset:-1792
	global_store_short_d16_hi v[14:15], v25, off offset:-1664
	v_add_f32_e32 v4, v26, v98
	v_add_f32_e32 v5, v27, v99
	v_bfe_u32 v20, v4, 16, 1
	v_bfe_u32 v21, v5, 16, 1
	v_mul_f32_e32 v22, v0, v5
	v_mul_f32_e32 v23, v0, v4
	v_add3_u32 v20, v4, v20, s9
	v_add3_u32 v21, v5, v21, s9
	v_fma_f32 v22, v2, v4, -v22
	v_fma_f32 v23, v2, v5, v23
	global_store_short_d16_hi v[14:15], v20, off offset:-1536
	global_store_short_d16_hi v[14:15], v21, off offset:-1408
	v_add_f32_e32 v4, v22, v100
	v_add_f32_e32 v5, v23, v101
	v_bfe_u32 v24, v4, 16, 1
	v_bfe_u32 v25, v5, 16, 1
	v_mul_f32_e32 v26, v0, v5
	v_mul_f32_e32 v27, v0, v4
	v_add3_u32 v24, v4, v24, s9
	v_add3_u32 v25, v5, v25, s9
	v_fma_f32 v26, v2, v4, -v26
	v_fma_f32 v27, v2, v5, v27
	global_store_short_d16_hi v[14:15], v24, off offset:-1280
	global_store_short_d16_hi v[14:15], v25, off offset:-1152
	v_add_f32_e32 v4, v26, v102
	v_add_f32_e32 v5, v27, v103
	v_bfe_u32 v20, v4, 16, 1
	v_bfe_u32 v21, v5, 16, 1
	v_mul_f32_e32 v22, v0, v5
	v_mul_f32_e32 v23, v0, v4
	v_add3_u32 v20, v4, v20, s9
	v_add3_u32 v21, v5, v21, s9
	v_fma_f32 v22, v2, v4, -v22
	v_fma_f32 v23, v2, v5, v23
	global_store_short_d16_hi v[14:15], v20, off offset:-1024
	global_store_short_d16_hi v[14:15], v21, off offset:-896
	v_add_f32_e32 v4, v22, v104
	v_add_f32_e32 v5, v23, v105
	v_bfe_u32 v24, v4, 16, 1
	v_bfe_u32 v25, v5, 16, 1
	v_mul_f32_e32 v26, v0, v5
	v_mul_f32_e32 v27, v0, v4
	v_add3_u32 v24, v4, v24, s9
	v_add3_u32 v25, v5, v25, s9
	v_fma_f32 v26, v2, v4, -v26
	v_fma_f32 v27, v2, v5, v27
	global_store_short_d16_hi v[14:15], v24, off offset:-768
	global_store_short_d16_hi v[14:15], v25, off offset:-640
	v_add_f32_e32 v4, v26, v106
	v_add_f32_e32 v5, v27, v107
	v_bfe_u32 v20, v4, 16, 1
	v_bfe_u32 v21, v5, 16, 1
	v_mul_f32_e32 v22, v0, v5
	v_mul_f32_e32 v23, v0, v4
	v_add3_u32 v20, v4, v20, s9
	v_add3_u32 v21, v5, v21, s9
	v_fma_f32 v22, v2, v4, -v22
	v_fma_f32 v23, v2, v5, v23
	global_store_short_d16_hi v[14:15], v20, off offset:-512
	global_store_short_d16_hi v[14:15], v21, off offset:-384
	v_add_f32_e32 v4, v22, v108
	v_add_f32_e32 v5, v23, v109
	v_bfe_u32 v24, v4, 16, 1
	v_bfe_u32 v25, v5, 16, 1
	v_mul_f32_e32 v26, v0, v5
	v_mul_f32_e32 v27, v0, v4
	v_add3_u32 v24, v4, v24, s9
	v_add3_u32 v25, v5, v25, s9
	v_fma_f32 v26, v2, v4, -v26
	v_fma_f32 v27, v2, v5, v27
	global_store_short_d16_hi v[14:15], v24, off offset:-256
	global_store_short_d16_hi v[14:15], v25, off offset:-128
	v_add_f32_e32 v4, v26, v110
	v_add_f32_e32 v5, v27, v111
	v_bfe_u32 v20, v4, 16, 1
	v_bfe_u32 v21, v5, 16, 1
	v_mul_f32_e32 v22, v0, v5
	v_mul_f32_e32 v23, v0, v4
	v_add3_u32 v20, v4, v20, s9
	v_add3_u32 v21, v5, v21, s9
	v_fma_f32 v22, v2, v4, -v22
	v_fma_f32 v23, v2, v5, v23
	global_store_short_d16_hi v[14:15], v20, off
	global_store_short_d16_hi v[14:15], v21, off offset:128
	v_add_f32_e32 v4, v22, v112
	v_add_f32_e32 v5, v23, v113
	v_bfe_u32 v24, v4, 16, 1
	v_bfe_u32 v25, v5, 16, 1
	v_mul_f32_e32 v26, v0, v5
	v_mul_f32_e32 v27, v0, v4
	v_add3_u32 v24, v4, v24, s9
	v_add3_u32 v25, v5, v25, s9
	v_fma_f32 v26, v2, v4, -v26
	v_fma_f32 v27, v2, v5, v27
	global_store_short_d16_hi v[14:15], v24, off offset:256
	global_store_short_d16_hi v[14:15], v25, off offset:384
	v_add_f32_e32 v4, v26, v114
	v_add_f32_e32 v5, v27, v115
	v_bfe_u32 v20, v4, 16, 1
	v_bfe_u32 v21, v5, 16, 1
	v_mul_f32_e32 v22, v0, v5
	v_mul_f32_e32 v23, v0, v4
	v_add3_u32 v20, v4, v20, s9
	v_add3_u32 v21, v5, v21, s9
	v_fma_f32 v22, v2, v4, -v22
	v_fma_f32 v23, v2, v5, v23
	global_store_short_d16_hi v[14:15], v20, off offset:512
	global_store_short_d16_hi v[14:15], v21, off offset:640
	v_add_f32_e32 v4, v22, v116
; #define LBAR() do { asm volatile("s_waitcnt lgkmcnt(0)" ::: "memory"); __builtin_amdgcn_s_barrier(); asm volatile("" ::: "memory"); } while (0)
; #define S5_LOAD(SR, SI, cb) do { _Pragma("unroll") for (int i = 0; i < 16; ++i) { SR[i] = sc[(size_t)((cb) + i) * 128 + n]; SI[i] = sc[(size_t)((cb) + i) * 128 + 64 + n]; } } while (0)
; #define S5_ACC(SR, SI) do { _Pragma("unroll") for (int i = 0; i < 16; ++i) { const float nhr = atr * hr - ati * hi + SR[i], nhi = atr * hi + ati * hr + SI[i]; hr = nhr; hi = nhi; } } while (0)
; #define S5_STEP(SR, SI, cb) do { _Pragma("unroll") for (int i = 0; i < 16; ++i) { \
;         hp[(size_t)((cb) + i) * 128 + n] = (bf16)f2bf(hr); hp[(size_t)((cb) + i) * 128 + 64 + n] = (bf16)f2bf(hi); \
;         const float nhr = atr * hr - ati * hi + SR[i], nhi = atr * hi + ati * hr + SI[i]; hr = nhr; hi = nhi; } } while (0)
; __device__ __forceinline__ void s5_scan_block(LAS unsigned char* lds, const Args& a, const float* __restrict__ SC, bf16* HP, int g, int wave, int lane) {
;     ...
;     float hr = 0.f, hi = 0.f;
;     for (int cb = 0; cb < 64; cb += 16) { S5_LOAD(sr0, si0, cb); S5_ACC(sr0, si0); }
;     LBAR();
;     ex[wave * 128 + n] = hr; ex[wave * 128 + 64 + n] = hi;
;     LBAR();
;     hr = 0.f; hi = 0.f;
;     for (int w = 0; w < wave; ++w) { const float er = ex[w * 128 + n], ei = ex[w * 128 + 64 + n]; const float nhr = asr * hr - asi * hi + er, nhi = asr * hi + asi * hr + ei; hr = nhr; hi = nhi; }
;     for (int cb = 0; cb < 64; cb += 16) { S5_LOAD(sr0, si0, cb); S5_STEP(sr0, si0, cb); }
	v_add_f32_e32 v5, v23, v117
	v_bfe_u32 v24, v4, 16, 1
	v_bfe_u32 v25, v5, 16, 1
	v_mul_f32_e32 v26, v0, v5
	v_mul_f32_e32 v27, v0, v4
	v_add3_u32 v24, v4, v24, s9
	v_add3_u32 v25, v5, v25, s9
	v_fma_f32 v26, v2, v4, -v26
	v_fma_f32 v27, v2, v5, v27
	global_store_short_d16_hi v[14:15], v24, off offset:768
	global_store_short_d16_hi v[14:15], v25, off offset:896
	v_add_f32_e32 v4, v26, v118
	v_add_f32_e32 v5, v27, v119
	v_bfe_u32 v20, v4, 16, 1
	v_bfe_u32 v21, v5, 16, 1
	v_mul_f32_e32 v22, v0, v5
	v_mul_f32_e32 v23, v0, v4
	v_add3_u32 v20, v4, v20, s9
	v_add3_u32 v21, v5, v21, s9
	v_fma_f32 v22, v2, v4, -v22
	v_fma_f32 v23, v2, v5, v23
	global_store_short_d16_hi v[14:15], v20, off offset:1024
	global_store_short_d16_hi v[14:15], v21, off offset:1152
	v_add_f32_e32 v4, v22, v120
	v_add_f32_e32 v5, v23, v121
	v_bfe_u32 v24, v4, 16, 1
	v_bfe_u32 v25, v5, 16, 1
	v_mul_f32_e32 v26, v0, v5
	v_mul_f32_e32 v27, v0, v4
	v_add3_u32 v24, v4, v24, s9
	v_add3_u32 v25, v5, v25, s9
	v_fma_f32 v26, v2, v4, -v26
	v_fma_f32 v27, v2, v5, v27
	global_store_short_d16_hi v[14:15], v24, off offset:1280
	global_store_short_d16_hi v[14:15], v25, off offset:1408
	v_add_f32_e32 v4, v26, v122
	v_add_f32_e32 v5, v27, v123
	v_bfe_u32 v20, v4, 16, 1
	v_bfe_u32 v21, v5, 16, 1
	v_mul_f32_e32 v22, v0, v5
	v_mul_f32_e32 v23, v0, v4
	v_add3_u32 v20, v4, v20, s9
	v_add3_u32 v21, v5, v21, s9
	v_fma_f32 v22, v2, v4, -v22
	v_fma_f32 v23, v2, v5, v23
	global_store_short_d16_hi v[14:15], v20, off offset:1536
	global_store_short_d16_hi v[14:15], v21, off offset:1664
	v_add_f32_e32 v4, v22, v124
	v_add_f32_e32 v5, v23, v125
	v_bfe_u32 v24, v4, 16, 1
	v_bfe_u32 v25, v5, 16, 1
	v_mul_f32_e32 v26, v0, v5
	v_mul_f32_e32 v27, v0, v4
	v_add3_u32 v24, v4, v24, s9
	v_add3_u32 v25, v5, v25, s9
	v_fma_f32 v26, v2, v4, -v26
	v_fma_f32 v27, v2, v5, v27
	global_store_short_d16_hi v[14:15], v24, off offset:1792
	global_store_short_d16_hi v[14:15], v25, off offset:1920
	v_add_f32_e32 v4, v26, v126
	v_add_f32_e32 v5, v27, v127
	v_lshl_add_u64 v[14:15], v[14:15], 0, s[2:3]
	v_bfe_u32 v20, v4, 16, 1
	v_bfe_u32 v21, v5, 16, 1
	v_mul_f32_e32 v22, v0, v5
	v_mul_f32_e32 v23, v0, v4
	v_add3_u32 v20, v4, v20, s9
	v_add3_u32 v21, v5, v21, s9
	v_fma_f32 v22, v2, v4, -v22
	v_fma_f32 v23, v2, v5, v23
	global_store_short_d16_hi v[14:15], v20, off offset:-2048
	global_store_short_d16_hi v[14:15], v21, off offset:-1920
	v_add_f32_e32 v4, v22, v128
	v_add_f32_e32 v5, v23, v129
	v_bfe_u32 v24, v4, 16, 1
	v_bfe_u32 v25, v5, 16, 1
	v_mul_f32_e32 v26, v0, v5
	v_mul_f32_e32 v27, v0, v4
	v_add3_u32 v24, v4, v24, s9
	v_add3_u32 v25, v5, v25, s9
	v_fma_f32 v26, v2, v4, -v26
	v_fma_f32 v27, v2, v5, v27
	global_store_short_d16_hi v[14:15], v24, off offset:-1792
	global_store_short_d16_hi v[14:15], v25, off offset:-1664
	v_add_f32_e32 v4, v26, v130
	v_add_f32_e32 v5, v27, v131
	v_bfe_u32 v20, v4, 16, 1
	v_bfe_u32 v21, v5, 16, 1
	v_mul_f32_e32 v22, v0, v5
	v_mul_f32_e32 v23, v0, v4
	v_add3_u32 v20, v4, v20, s9
	v_add3_u32 v21, v5, v21, s9
	v_fma_f32 v22, v2, v4, -v22
	v_fma_f32 v23, v2, v5, v23
	global_store_short_d16_hi v[14:15], v20, off offset:-1536
	global_store_short_d16_hi v[14:15], v21, off offset:-1408
	v_add_f32_e32 v4, v22, v132
	v_add_f32_e32 v5, v23, v133
	v_bfe_u32 v24, v4, 16, 1
	v_bfe_u32 v25, v5, 16, 1
	v_mul_f32_e32 v26, v0, v5
	v_mul_f32_e32 v27, v0, v4
	v_add3_u32 v24, v4, v24, s9
	v_add3_u32 v25, v5, v25, s9
	v_fma_f32 v26, v2, v4, -v26
	v_fma_f32 v27, v2, v5, v27
	global_store_short_d16_hi v[14:15], v24, off offset:-1280
	global_store_short_d16_hi v[14:15], v25, off offset:-1152
	v_add_f32_e32 v4, v26, v134
	v_add_f32_e32 v5, v27, v135
	v_bfe_u32 v20, v4, 16, 1
	v_bfe_u32 v21, v5, 16, 1
	v_mul_f32_e32 v22, v0, v5
	v_mul_f32_e32 v23, v0, v4
	v_add3_u32 v20, v4, v20, s9
	v_add3_u32 v21, v5, v21, s9
	v_fma_f32 v22, v2, v4, -v22
	v_fma_f32 v23, v2, v5, v23
	global_store_short_d16_hi v[14:15], v20, off offset:-1024
	global_store_short_d16_hi v[14:15], v21, off offset:-896
	v_add_f32_e32 v4, v22, v136
	v_add_f32_e32 v5, v23, v137
	v_bfe_u32 v24, v4, 16, 1
	v_bfe_u32 v25, v5, 16, 1
	v_mul_f32_e32 v26, v0, v5
	v_mul_f32_e32 v27, v0, v4
	v_add3_u32 v24, v4, v24, s9
	v_add3_u32 v25, v5, v25, s9
	v_fma_f32 v26, v2, v4, -v26
	v_fma_f32 v27, v2, v5, v27
	global_store_short_d16_hi v[14:15], v24, off offset:-768
	global_store_short_d16_hi v[14:15], v25, off offset:-640
	v_add_f32_e32 v4, v26, v138
	v_add_f32_e32 v5, v27, v139
	v_bfe_u32 v20, v4, 16, 1
	v_bfe_u32 v21, v5, 16, 1
	v_mul_f32_e32 v22, v0, v5
	v_mul_f32_e32 v23, v0, v4
	v_add3_u32 v20, v4, v20, s9
	v_add3_u32 v21, v5, v21, s9
	v_fma_f32 v22, v2, v4, -v22
	v_fma_f32 v23, v2, v5, v23
	global_store_short_d16_hi v[14:15], v20, off offset:-512
	global_store_short_d16_hi v[14:15], v21, off offset:-384
	v_add_f32_e32 v4, v22, v140
	v_add_f32_e32 v5, v23, v141
	v_bfe_u32 v24, v4, 16, 1
	v_bfe_u32 v25, v5, 16, 1
	v_mul_f32_e32 v26, v0, v5
	v_mul_f32_e32 v27, v0, v4
	v_add3_u32 v24, v4, v24, s9
	v_add3_u32 v25, v5, v25, s9
	v_fma_f32 v26, v2, v4, -v26
	v_fma_f32 v27, v2, v5, v27
	global_store_short_d16_hi v[14:15], v24, off offset:-256
	global_store_short_d16_hi v[14:15], v25, off offset:-128
	v_add_f32_e32 v4, v26, v142
	v_add_f32_e32 v5, v27, v143
	v_bfe_u32 v20, v4, 16, 1
	v_bfe_u32 v21, v5, 16, 1
	v_mul_f32_e32 v22, v0, v5
	v_mul_f32_e32 v23, v0, v4
	v_add3_u32 v20, v4, v20, s9
	v_add3_u32 v21, v5, v21, s9
	v_fma_f32 v22, v2, v4, -v22
	v_fma_f32 v23, v2, v5, v23
	global_store_short_d16_hi v[14:15], v20, off
	global_store_short_d16_hi v[14:15], v21, off offset:128
	v_add_f32_e32 v4, v22, v144
	v_add_f32_e32 v5, v23, v145
	v_bfe_u32 v24, v4, 16, 1
	v_bfe_u32 v25, v5, 16, 1
; #define LBAR() do { asm volatile("s_waitcnt lgkmcnt(0)" ::: "memory"); __builtin_amdgcn_s_barrier(); asm volatile("" ::: "memory"); } while (0)
; #define S5_LOAD(SR, SI, cb) do { _Pragma("unroll") for (int i = 0; i < 16; ++i) { SR[i] = sc[(size_t)((cb) + i) * 128 + n]; SI[i] = sc[(size_t)((cb) + i) * 128 + 64 + n]; } } while (0)
; #define S5_ACC(SR, SI) do { _Pragma("unroll") for (int i = 0; i < 16; ++i) { const float nhr = atr * hr - ati * hi + SR[i], nhi = atr * hi + ati * hr + SI[i]; hr = nhr; hi = nhi; } } while (0)
; #define S5_STEP(SR, SI, cb) do { _Pragma("unroll") for (int i = 0; i < 16; ++i) { \
;         hp[(size_t)((cb) + i) * 128 + n] = (bf16)f2bf(hr); hp[(size_t)((cb) + i) * 128 + 64 + n] = (bf16)f2bf(hi); \
;         const float nhr = atr * hr - ati * hi + SR[i], nhi = atr * hi + ati * hr + SI[i]; hr = nhr; hi = nhi; } } while (0)
; __device__ __forceinline__ void s5_scan_block(LAS unsigned char* lds, const Args& a, const float* __restrict__ SC, bf16* HP, int g, int wave, int lane) {
;     ...
;     float hr = 0.f, hi = 0.f;
;     for (int cb = 0; cb < 64; cb += 16) { S5_LOAD(sr0, si0, cb); S5_ACC(sr0, si0); }
;     LBAR();
;     ex[wave * 128 + n] = hr; ex[wave * 128 + 64 + n] = hi;
;     LBAR();
;     hr = 0.f; hi = 0.f;
;     for (int w = 0; w < wave; ++w) { const float er = ex[w * 128 + n], ei = ex[w * 128 + 64 + n]; const float nhr = asr * hr - asi * hi + er, nhi = asr * hi + asi * hr + ei; hr = nhr; hi = nhi; }
;     for (int cb = 0; cb < 64; cb += 16) { S5_LOAD(sr0, si0, cb); S5_STEP(sr0, si0, cb); }
	v_mul_f32_e32 v26, v0, v5
	v_mul_f32_e32 v27, v0, v4
	v_add3_u32 v24, v4, v24, s9
	v_add3_u32 v25, v5, v25, s9
	v_fma_f32 v26, v2, v4, -v26
	v_fma_f32 v27, v2, v5, v27
	global_store_short_d16_hi v[14:15], v24, off offset:256
	global_store_short_d16_hi v[14:15], v25, off offset:384
	v_add_f32_e32 v4, v26, v146
	v_add_f32_e32 v5, v27, v147
	v_bfe_u32 v20, v4, 16, 1
	v_bfe_u32 v21, v5, 16, 1
	v_mul_f32_e32 v22, v0, v5
	v_mul_f32_e32 v23, v0, v4
	v_add3_u32 v20, v4, v20, s9
	v_add3_u32 v21, v5, v21, s9
	v_fma_f32 v22, v2, v4, -v22
	v_fma_f32 v23, v2, v5, v23
	global_store_short_d16_hi v[14:15], v20, off offset:512
	global_store_short_d16_hi v[14:15], v21, off offset:640
	v_add_f32_e32 v4, v22, v148
	v_add_f32_e32 v5, v23, v149
	v_bfe_u32 v24, v4, 16, 1
	v_bfe_u32 v25, v5, 16, 1
	v_mul_f32_e32 v26, v0, v5
	v_mul_f32_e32 v27, v0, v4
	v_add3_u32 v24, v4, v24, s9
	v_add3_u32 v25, v5, v25, s9
	v_fma_f32 v26, v2, v4, -v26
	v_fma_f32 v27, v2, v5, v27
	global_store_short_d16_hi v[14:15], v24, off offset:768
	global_store_short_d16_hi v[14:15], v25, off offset:896
	v_add_f32_e32 v4, v26, v150
	v_add_f32_e32 v5, v27, v151
	v_bfe_u32 v20, v4, 16, 1
	v_bfe_u32 v21, v5, 16, 1
	v_mul_f32_e32 v22, v0, v5
	v_mul_f32_e32 v23, v0, v4
	v_add3_u32 v20, v4, v20, s9
	v_add3_u32 v21, v5, v21, s9
	v_fma_f32 v22, v2, v4, -v22
	v_fma_f32 v23, v2, v5, v23
	global_store_short_d16_hi v[14:15], v20, off offset:1024
	global_store_short_d16_hi v[14:15], v21, off offset:1152
	v_add_f32_e32 v4, v22, v152
	v_add_f32_e32 v5, v23, v153
	v_bfe_u32 v24, v4, 16, 1
	v_bfe_u32 v25, v5, 16, 1
	v_mul_f32_e32 v26, v0, v5
	v_mul_f32_e32 v27, v0, v4
	v_add3_u32 v24, v4, v24, s9
	v_add3_u32 v25, v5, v25, s9
	v_fma_f32 v26, v2, v4, -v26
	v_fma_f32 v27, v2, v5, v27
	global_store_short_d16_hi v[14:15], v24, off offset:1280
	global_store_short_d16_hi v[14:15], v25, off offset:1408
	v_add_f32_e32 v4, v26, v154
	v_add_f32_e32 v5, v27, v155
	v_bfe_u32 v20, v4, 16, 1
	v_bfe_u32 v21, v5, 16, 1
	v_mul_f32_e32 v22, v0, v5
	v_mul_f32_e32 v23, v0, v4
	v_add3_u32 v20, v4, v20, s9
	v_add3_u32 v21, v5, v21, s9
	v_fma_f32 v22, v2, v4, -v22
	v_fma_f32 v23, v2, v5, v23
	global_store_short_d16_hi v[14:15], v20, off offset:1536
	global_store_short_d16_hi v[14:15], v21, off offset:1664
	v_add_f32_e32 v4, v22, v156
	v_add_f32_e32 v5, v23, v157
	v_bfe_u32 v24, v4, 16, 1
	v_bfe_u32 v25, v5, 16, 1
	v_mul_f32_e32 v26, v0, v5
	v_mul_f32_e32 v27, v0, v4
	v_add3_u32 v24, v4, v24, s9
	v_add3_u32 v25, v5, v25, s9
	v_fma_f32 v26, v2, v4, -v26
	v_fma_f32 v27, v2, v5, v27
	global_store_short_d16_hi v[14:15], v24, off offset:1792
	global_store_short_d16_hi v[14:15], v25, off offset:1920
	v_add_f32_e32 v4, v26, v158
	v_add_f32_e32 v5, v27, v159
	v_lshl_add_u64 v[14:15], v[14:15], 0, s[2:3]
	v_bfe_u32 v20, v4, 16, 1
	v_bfe_u32 v21, v5, 16, 1
	v_mul_f32_e32 v22, v0, v5
	v_mul_f32_e32 v23, v0, v4
	v_add3_u32 v20, v4, v20, s9
	v_add3_u32 v21, v5, v21, s9
	v_fma_f32 v22, v2, v4, -v22
	v_fma_f32 v23, v2, v5, v23
	global_store_short_d16_hi v[14:15], v20, off offset:-2048
	global_store_short_d16_hi v[14:15], v21, off offset:-1920
	v_add_f32_e32 v4, v22, v160
	v_add_f32_e32 v5, v23, v161
	v_bfe_u32 v24, v4, 16, 1
	v_bfe_u32 v25, v5, 16, 1
	v_mul_f32_e32 v26, v0, v5
	v_mul_f32_e32 v27, v0, v4
	v_add3_u32 v24, v4, v24, s9
	v_add3_u32 v25, v5, v25, s9
	v_fma_f32 v26, v2, v4, -v26
	v_fma_f32 v27, v2, v5, v27
	global_store_short_d16_hi v[14:15], v24, off offset:-1792
	global_store_short_d16_hi v[14:15], v25, off offset:-1664
	v_add_f32_e32 v4, v26, v162
	v_add_f32_e32 v5, v27, v163
	v_bfe_u32 v20, v4, 16, 1
	v_bfe_u32 v21, v5, 16, 1
	v_mul_f32_e32 v22, v0, v5
	v_mul_f32_e32 v23, v0, v4
	v_add3_u32 v20, v4, v20, s9
	v_add3_u32 v21, v5, v21, s9
	v_fma_f32 v22, v2, v4, -v22
	v_fma_f32 v23, v2, v5, v23
	global_store_short_d16_hi v[14:15], v20, off offset:-1536
	global_store_short_d16_hi v[14:15], v21, off offset:-1408
	v_add_f32_e32 v4, v22, v164
	v_add_f32_e32 v5, v23, v165
	v_bfe_u32 v24, v4, 16, 1
	v_bfe_u32 v25, v5, 16, 1
	v_mul_f32_e32 v26, v0, v5
	v_mul_f32_e32 v27, v0, v4
	v_add3_u32 v24, v4, v24, s9
	v_add3_u32 v25, v5, v25, s9
	v_fma_f32 v26, v2, v4, -v26
	v_fma_f32 v27, v2, v5, v27
	global_store_short_d16_hi v[14:15], v24, off offset:-1280
	global_store_short_d16_hi v[14:15], v25, off offset:-1152
	v_add_f32_e32 v4, v26, v166
	v_add_f32_e32 v5, v27, v167
	v_bfe_u32 v20, v4, 16, 1
	v_bfe_u32 v21, v5, 16, 1
	v_mul_f32_e32 v22, v0, v5
	v_mul_f32_e32 v23, v0, v4
	v_add3_u32 v20, v4, v20, s9
	v_add3_u32 v21, v5, v21, s9
	v_fma_f32 v22, v2, v4, -v22
	v_fma_f32 v23, v2, v5, v23
	global_store_short_d16_hi v[14:15], v20, off offset:-1024
	global_store_short_d16_hi v[14:15], v21, off offset:-896
	v_add_f32_e32 v4, v22, v168
	v_add_f32_e32 v5, v23, v169
	v_bfe_u32 v24, v4, 16, 1
; #define LBAR() do { asm volatile("s_waitcnt lgkmcnt(0)" ::: "memory"); __builtin_amdgcn_s_barrier(); asm volatile("" ::: "memory"); } while (0)
; #define S5_LOAD(SR, SI, cb) do { _Pragma("unroll") for (int i = 0; i < 16; ++i) { SR[i] = sc[(size_t)((cb) + i) * 128 + n]; SI[i] = sc[(size_t)((cb) + i) * 128 + 64 + n]; } } while (0)
; #define S5_ACC(SR, SI) do { _Pragma("unroll") for (int i = 0; i < 16; ++i) { const float nhr = atr * hr - ati * hi + SR[i], nhi = atr * hi + ati * hr + SI[i]; hr = nhr; hi = nhi; } } while (0)
; #define S5_STEP(SR, SI, cb) do { _Pragma("unroll") for (int i = 0; i < 16; ++i) { \
;         hp[(size_t)((cb) + i) * 128 + n] = (bf16)f2bf(hr); hp[(size_t)((cb) + i) * 128 + 64 + n] = (bf16)f2bf(hi); \
;         const float nhr = atr * hr - ati * hi + SR[i], nhi = atr * hi + ati * hr + SI[i]; hr = nhr; hi = nhi; } } while (0)
; __device__ __forceinline__ void s5_scan_block(LAS unsigned char* lds, const Args& a, const float* __restrict__ SC, bf16* HP, int g, int wave, int lane) {
;     ...
;     float hr = 0.f, hi = 0.f;
;     for (int cb = 0; cb < 64; cb += 16) { S5_LOAD(sr0, si0, cb); S5_ACC(sr0, si0); }
;     LBAR();
;     ex[wave * 128 + n] = hr; ex[wave * 128 + 64 + n] = hi;
;     LBAR();
;     hr = 0.f; hi = 0.f;
;     for (int w = 0; w < wave; ++w) { const float er = ex[w * 128 + n], ei = ex[w * 128 + 64 + n]; const float nhr = asr * hr - asi * hi + er, nhi = asr * hi + asi * hr + ei; hr = nhr; hi = nhi; }
;     for (int cb = 0; cb < 64; cb += 16) { S5_LOAD(sr0, si0, cb); S5_STEP(sr0, si0, cb); }
; __global__ void __launch_bounds__(512, 2) mega(Args a) {
;     ...
;                 asm volatile("s_waitcnt vmcnt(0)" ::: "memory");
;                 __syncthreads();
;                 if (tid == 0) { __builtin_amdgcn_fence(__ATOMIC_RELEASE, "agent"); asm volatile("s_waitcnt vmcnt(0)" ::: "memory"); __hip_atomic_store(flg + 64 * b, 1u, __ATOMIC_RELAXED, __HIP_MEMORY_SCOPE_AGENT); }
	v_bfe_u32 v25, v5, 16, 1
	v_mul_f32_e32 v26, v0, v5
	v_mul_f32_e32 v27, v0, v4
	v_add3_u32 v24, v4, v24, s9
	v_add3_u32 v25, v5, v25, s9
	v_fma_f32 v26, v2, v4, -v26
	v_fma_f32 v27, v2, v5, v27
	global_store_short_d16_hi v[14:15], v24, off offset:-768
	global_store_short_d16_hi v[14:15], v25, off offset:-640
	v_add_f32_e32 v4, v26, v170
	v_add_f32_e32 v5, v27, v171
	v_bfe_u32 v20, v4, 16, 1
	v_bfe_u32 v21, v5, 16, 1
	v_mul_f32_e32 v22, v0, v5
	v_mul_f32_e32 v23, v0, v4
	v_add3_u32 v20, v4, v20, s9
	v_add3_u32 v21, v5, v21, s9
	v_fma_f32 v22, v2, v4, -v22
	v_fma_f32 v23, v2, v5, v23
	global_store_short_d16_hi v[14:15], v20, off offset:-512
	global_store_short_d16_hi v[14:15], v21, off offset:-384
	v_add_f32_e32 v4, v22, v172
	v_add_f32_e32 v5, v23, v173
	v_bfe_u32 v24, v4, 16, 1
	v_bfe_u32 v25, v5, 16, 1
	v_mul_f32_e32 v26, v0, v5
	v_mul_f32_e32 v27, v0, v4
	v_add3_u32 v24, v4, v24, s9
	v_add3_u32 v25, v5, v25, s9
	v_fma_f32 v26, v2, v4, -v26
	v_fma_f32 v27, v2, v5, v27
	global_store_short_d16_hi v[14:15], v24, off offset:-256
	global_store_short_d16_hi v[14:15], v25, off offset:-128
	v_add_f32_e32 v4, v26, v174
	v_add_f32_e32 v5, v27, v175
	v_bfe_u32 v20, v4, 16, 1
	v_bfe_u32 v21, v5, 16, 1
	v_mul_f32_e32 v22, v0, v5
	v_mul_f32_e32 v23, v0, v4
	v_add3_u32 v20, v4, v20, s9
	v_add3_u32 v21, v5, v21, s9
	v_fma_f32 v22, v2, v4, -v22
	v_fma_f32 v23, v2, v5, v23
	global_store_short_d16_hi v[14:15], v20, off
	global_store_short_d16_hi v[14:15], v21, off offset:128
	v_add_f32_e32 v4, v22, v176
	v_add_f32_e32 v5, v23, v177
	v_bfe_u32 v24, v4, 16, 1
	v_bfe_u32 v25, v5, 16, 1
	v_mul_f32_e32 v26, v0, v5
	v_mul_f32_e32 v27, v0, v4
	v_add3_u32 v24, v4, v24, s9
	v_add3_u32 v25, v5, v25, s9
	v_fma_f32 v26, v2, v4, -v26
	v_fma_f32 v27, v2, v5, v27
	global_store_short_d16_hi v[14:15], v24, off offset:256
	global_store_short_d16_hi v[14:15], v25, off offset:384
	v_add_f32_e32 v4, v26, v178
	v_add_f32_e32 v5, v27, v179
	v_bfe_u32 v20, v4, 16, 1
	v_bfe_u32 v21, v5, 16, 1
	v_mul_f32_e32 v22, v0, v5
	v_mul_f32_e32 v23, v0, v4
	v_add3_u32 v20, v4, v20, s9
	v_add3_u32 v21, v5, v21, s9
	v_fma_f32 v22, v2, v4, -v22
	v_fma_f32 v23, v2, v5, v23
	global_store_short_d16_hi v[14:15], v20, off offset:512
	global_store_short_d16_hi v[14:15], v21, off offset:640
	v_add_f32_e32 v4, v22, v180
	v_add_f32_e32 v5, v23, v181
	v_bfe_u32 v24, v4, 16, 1
	v_bfe_u32 v25, v5, 16, 1
	v_mul_f32_e32 v26, v0, v5
	v_mul_f32_e32 v27, v0, v4
	v_add3_u32 v24, v4, v24, s9
	v_add3_u32 v25, v5, v25, s9
	v_fma_f32 v26, v2, v4, -v26
	v_fma_f32 v27, v2, v5, v27
	global_store_short_d16_hi v[14:15], v24, off offset:768
	global_store_short_d16_hi v[14:15], v25, off offset:896
	v_add_f32_e32 v4, v26, v182
	v_add_f32_e32 v5, v27, v183
	v_bfe_u32 v20, v4, 16, 1
	v_bfe_u32 v21, v5, 16, 1
	v_mul_f32_e32 v22, v0, v5
	v_mul_f32_e32 v23, v0, v4
	v_add3_u32 v20, v4, v20, s9
	v_add3_u32 v21, v5, v21, s9
	v_fma_f32 v22, v2, v4, -v22
	v_fma_f32 v23, v2, v5, v23
	global_store_short_d16_hi v[14:15], v20, off offset:1024
	global_store_short_d16_hi v[14:15], v21, off offset:1152
	v_add_f32_e32 v4, v22, v196
	v_add_f32_e32 v5, v23, v197
	v_bfe_u32 v24, v4, 16, 1
	v_bfe_u32 v25, v5, 16, 1
	v_mul_f32_e32 v26, v0, v5
	v_mul_f32_e32 v27, v0, v4
	v_add3_u32 v24, v4, v24, s9
	v_add3_u32 v25, v5, v25, s9
	v_fma_f32 v26, v2, v4, -v26
	v_fma_f32 v27, v2, v5, v27
	global_store_short_d16_hi v[14:15], v24, off offset:1280
	global_store_short_d16_hi v[14:15], v25, off offset:1408
	v_add_f32_e32 v4, v26, v198
	v_add_f32_e32 v5, v27, v199
	v_bfe_u32 v20, v4, 16, 1
	v_bfe_u32 v21, v5, 16, 1
	v_mul_f32_e32 v22, v0, v5
	v_mul_f32_e32 v23, v0, v4
	v_add3_u32 v20, v4, v20, s9
	v_add3_u32 v21, v5, v21, s9
	v_fma_f32 v22, v2, v4, -v22
	v_fma_f32 v23, v2, v5, v23
	global_store_short_d16_hi v[14:15], v20, off offset:1536
	global_store_short_d16_hi v[14:15], v21, off offset:1664
	v_add_f32_e32 v4, v22, v200
	v_add_f32_e32 v5, v23, v201
	v_bfe_u32 v24, v4, 16, 1
	v_bfe_u32 v25, v5, 16, 1
	v_mul_f32_e32 v26, v0, v5
	v_mul_f32_e32 v27, v0, v4
	v_add3_u32 v24, v4, v24, s9
	v_add3_u32 v25, v5, v25, s9
	v_fma_f32 v26, v2, v4, -v26
	v_fma_f32 v27, v2, v5, v27
	global_store_short_d16_hi v[14:15], v24, off offset:1792
	global_store_short_d16_hi v[14:15], v25, off offset:1920
	v_add_f32_e32 v4, v26, v202
	v_add_f32_e32 v5, v27, v203
	s_waitcnt vmcnt(0)
	s_waitcnt lgkmcnt(0)
	s_barrier
	s_mov_b64 s[0:1], exec
	v_readlane_b32 s2, v245, 5
	v_readlane_b32 s3, v245, 6
	s_and_b64 s[2:3], s[0:1], s[2:3]
	s_mov_b64 exec, s[2:3]
	s_cbranch_execz .LBB0_781
	s_ashr_i32 s9, s8, 31
	s_lshl_b64 s[2:3], s[8:9], 2
	buffer_wbl2 sc1
	s_waitcnt vmcnt(0)
	s_waitcnt vmcnt(0)
	s_add_u32 s2, s24, s2
	s_addc_u32 s3, s25, s3
	v_mov_b32_e32 v0, 0
	v_mov_b32_e32 v1, 1
	global_store_dword v0, v1, s[2:3] sc1

; __device__ __forceinline__ void attn_combine(unsigned char* ws, const float* __restrict__ PM, bf16* CAT, int gtid, int gthreads, int iend = S * 128) {
;     for (int idx = gtid; idx < iend; idx += gthreads) {
;         const int t = idx >> 7, c = (idx & 127) * 8, hh = c >> 7;
;         float mm[3], ll[3];
; #pragma unroll
;         for (int p = 0; p < 3; ++p) { const f32x2_t ml = *(const f32x2_t*)(PM + (((size_t)p * S + t) * 8 + hh) * 2); mm[p] = ml[0]; ll[p] = ml[1]; }
; __global__ void __launch_bounds__(512, 2) mega(Args a) {
;     ...
;             const long NIT = (long)S * 128, W = 192 * 5 + 64 * 3;
;             const long c0 = b <= NG ? 3L * b : 192L + 5L * (b - NG), c1 = (b + 1) <= NG ? 3L * (b + 1) : 192L + 5L * (b + 1 - NG);
;             const int i0 = (int)(NIT * c0 / W), i1 = (int)(NIT * c1 / W);
;             attn_combine(ws, PM, CAT, i0 + tid, 512, i1);
.LBB0_790:
	s_lshl_b64 s[4:5], s[0:1], 21
	s_lshr_b64 s[0:1], s[0:1], 11
	s_mul_hi_u32 s6, s4, 0xe38e38e
	s_mul_i32 s7, s4, 0xe38e38e
	s_mul_i32 s8, s0, 0x38e38e39
	s_mul_hi_u32 s4, s4, 0x38e38e39
	s_mul_hi_u32 s1, s0, 0x38e38e39
	s_add_u32 s4, s8, s4
	s_addc_u32 s1, s1, 0
	s_add_u32 s4, s7, s4
	s_addc_u32 s4, s6, 0
	s_add_u32 s1, s1, s4
	s_addc_u32 s4, 0, 0
	s_mul_hi_u32 s6, s0, 0xe38e38e
	s_mul_i32 s0, s0, 0xe38e38e
	s_add_u32 s0, s0, s1
	s_addc_u32 s1, s6, s4
	s_ashr_i32 s4, s5, 31
	s_mul_i32 s5, s4, 0xe38e38e
	s_mul_hi_u32 s6, s4, 0x38e38e39
	s_add_i32 s5, s6, s5
	s_mul_i32 s4, s4, 0x38e38e39
	s_add_i32 s5, s5, s4
	s_add_u32 s0, s0, s4
	s_addc_u32 s1, s1, s5
	s_lshr_b32 s4, s1, 31
	s_lshr_b64 s[0:1], s[0:1], 6
	s_add_i32 s4, s0, s4
	s_lshl_b64 s[0:1], s[2:3], 21
	s_lshr_b64 s[2:3], s[2:3], 11
	s_mul_hi_u32 s5, s0, 0xe38e38e
	s_mul_i32 s6, s0, 0xe38e38e
	s_mul_i32 s7, s2, 0x38e38e39
	s_mul_hi_u32 s0, s0, 0x38e38e39
	s_mul_hi_u32 s3, s2, 0x38e38e39
	s_add_u32 s0, s7, s0
	s_addc_u32 s3, s3, 0
	s_add_u32 s0, s6, s0
	s_addc_u32 s0, s5, 0
	s_add_u32 s0, s3, s0
	s_addc_u32 s3, 0, 0
	s_mul_hi_u32 s5, s2, 0xe38e38e
	s_mul_i32 s2, s2, 0xe38e38e
	s_add_u32 s0, s2, s0
	s_addc_u32 s2, s5, s3
	s_ashr_i32 s1, s1, 31
	s_mul_i32 s3, s1, 0xe38e38e
	s_mul_hi_u32 s5, s1, 0x38e38e39
	s_add_i32 s3, s5, s3
	s_mul_i32 s1, s1, 0x38e38e39
	s_add_i32 s3, s3, s1
	s_add_u32 s0, s0, s1
	s_addc_u32 s1, s2, s3
	s_lshr_b32 s2, s1, 31
	s_lshr_b64 s[0:1], s[0:1], 6
	s_add_i32 s18, s0, s2
	s_mov_b64 s[2:3], exec
	s_sub_i32 s0, s66, 64
	s_cmp_lt_i32 s0, 0
	s_cbranch_scc1 .Lcmb_skip
	s_lshl_b32 s4, s0, 15
	s_add_i32 s18, s4, 0x8000
	s_mul_hi_u32 s4, s4, 0xaaaaaaab
	s_lshr_b32 s4, s4, 1
	s_mul_hi_u32 s18, s18, 0xaaaaaaab
	s_lshr_b32 s18, s18, 1
	v_add_u32_e32 v2, s4, v186
	v_readlane_b32 s26, v245, 38
	v_readlane_b32 s27, v245, 39
	s_add_u32 s6, s88, 0x600000
	s_addc_u32 s7, s89, 0
	s_add_u32 s8, s88, 0x700000
	s_addc_u32 s9, s89, 0
	s_add_u32 s16, s88, 0x1b400000
	s_addc_u32 s17, s89, 0
	s_add_u32 s20, s88, 0x1d400000
	s_addc_u32 s21, s89, 0
	v_readlane_b32 s22, v245, 15
	v_readlane_b32 s23, v245, 16
	s_sub_i32 s0, s18, s4
	s_add_i32 s0, s0, 2047
	s_lshr_b32 s0, s0, 11
	s_add_i32 s1, s18, -1
	s_mov_b32 s19, 0xc2fc0000
	v_mov_b32_e32 v1, 0
	v_mov_b32_e32 v4, 0x42800000
	v_not_b32_e32 v5, 63
	v_min_i32_e32 v60, s1, v2
	v_ashrrev_i32_e32 v59, 7, v60
	v_lshrrev_b32_e32 v61, 1, v60
	v_and_b32_e32 v61, 56, v61
	v_lshl_or_b32 v61, v59, 6, v61
	global_load_dwordx2 v[40:41], v61, s[26:27]
	global_load_dwordx2 v[42:43], v61, s[6:7]
	global_load_dwordx2 v[44:45], v61, s[8:9]
	v_and_b32_e32 v58, 0x7f, v60
	v_lshlrev_b32_e32 v60, 4, v60
	v_lshlrev_b32_e32 v58, 4, v58
	global_load_dwordx4 v[46:49], v60, s[16:17]
	v_lshl_or_b32 v58, v59, 12, v58
	global_load_dwordx4 v[50:53], v60, s[20:21]
	global_load_dwordx4 v[54:57], v60, s[22:23]
	v_add_u32_e32 v84, 512, v2
	v_min_i32_e32 v84, s1, v84
	v_ashrrev_i32_e32 v83, 7, v84
	v_lshrrev_b32_e32 v85, 1, v84
	v_and_b32_e32 v85, 56, v85
	v_lshl_or_b32 v85, v83, 6, v85
	global_load_dwordx2 v[64:65], v85, s[26:27]
	global_load_dwordx2 v[66:67], v85, s[6:7]
	global_load_dwordx2 v[68:69], v85, s[8:9]
	v_and_b32_e32 v82, 0x7f, v84
	v_lshlrev_b32_e32 v84, 4, v84
	v_lshlrev_b32_e32 v82, 4, v82
	global_load_dwordx4 v[70:73], v84, s[16:17]
	v_lshl_or_b32 v82, v83, 12, v82
	global_load_dwordx4 v[74:77], v84, s[20:21]
	global_load_dwordx4 v[78:81], v84, s[22:23]
	v_add_u32_e32 v108, 1024, v2
	v_min_i32_e32 v108, s1, v108
	v_ashrrev_i32_e32 v107, 7, v108
	v_lshrrev_b32_e32 v109, 1, v108
	v_and_b32_e32 v109, 56, v109
	v_lshl_or_b32 v109, v107, 6, v109
	global_load_dwordx2 v[88:89], v109, s[26:27]
	global_load_dwordx2 v[90:91], v109, s[6:7]
	global_load_dwordx2 v[92:93], v109, s[8:9]
	v_and_b32_e32 v106, 0x7f, v108
	v_lshlrev_b32_e32 v108, 4, v108
	v_lshlrev_b32_e32 v106, 4, v106
	global_load_dwordx4 v[94:97], v108, s[16:17]
	v_lshl_or_b32 v106, v107, 12, v106
	global_load_dwordx4 v[98:101], v108, s[20:21]
	global_load_dwordx4 v[102:105], v108, s[22:23]
	v_add_u32_e32 v132, 1536, v2
	v_min_i32_e32 v132, s1, v132
	v_ashrrev_i32_e32 v131, 7, v132
	v_lshrrev_b32_e32 v133, 1, v132
	v_and_b32_e32 v133, 56, v133
	v_lshl_or_b32 v133, v131, 6, v133
	global_load_dwordx2 v[112:113], v133, s[26:27]
	global_load_dwordx2 v[114:115], v133, s[6:7]
	global_load_dwordx2 v[116:117], v133, s[8:9]
	v_and_b32_e32 v130, 0x7f, v132
	v_lshlrev_b32_e32 v132, 4, v132
	v_lshlrev_b32_e32 v130, 4, v130
	global_load_dwordx4 v[118:121], v132, s[16:17]
	v_lshl_or_b32 v130, v131, 12, v130
	global_load_dwordx4 v[122:125], v132, s[20:21]
	global_load_dwordx4 v[126:129], v132, s[22:23]
	v_add_u32_e32 v2, 2048, v2
; __device__ __forceinline__ unsigned pk2(float lo, float hi) { f32x2_t v = {lo, hi}; bf16x2_t b = __builtin_convertvector(v, bf16x2_t); return __builtin_bit_cast(unsigned, b); }
; __device__ __forceinline__ float bflo(unsigned w) { return __uint_as_float(w << 16); }
; __device__ __forceinline__ float bfhi(unsigned w) { return __uint_as_float(w & 0xffff0000u); }
; __device__ __forceinline__ bf16* po_base(unsigned char* ws, int pat) { return (bf16*)(ws + (pat < 2 ? 436 * MiB + (size_t)pat * 32 * MiB : WS_Y)); }
; __device__ __forceinline__ void attn_combine(unsigned char* ws, const float* __restrict__ PM, bf16* CAT, int gtid, int gthreads, int iend = S * 128) {
;     for (int idx = gtid; idx < iend; idx += gthreads) {
;         const int t = idx >> 7, c = (idx & 127) * 8, hh = c >> 7;
;         float mm[3], ll[3];
; #pragma unroll
;         for (int p = 0; p < 3; ++p) { const f32x2_t ml = *(const f32x2_t*)(PM + (((size_t)p * S + t) * 8 + hh) * 2); mm[p] = ml[0]; ll[p] = ml[1]; }
;         const float ma = fmaxf(mm[0], fmaxf(mm[1], mm[2]));
;         float w[3], den = 0.f;
; #pragma unroll
;         for (int p = 0; p < 3; ++p) { w[p] = exp2f(mm[p] - ma) * ll[p]; den += w[p]; }
;         const float inv = 1.f / den;
;         float o[8] = {0.f, 0.f, 0.f, 0.f, 0.f, 0.f, 0.f, 0.f};
; #pragma unroll
;         for (int p = 0; p < 3; ++p) {
;             const u32x4 v = *(const u32x4*)(po_base(ws, p) + (size_t)t * 1024 + c); const float wp = w[p] * inv;
;             o[0] += wp * bflo(v.x); o[1] += wp * bfhi(v.x); o[2] += wp * bflo(v.y); o[3] += wp * bfhi(v.y); o[4] += wp * bflo(v.z); o[5] += wp * bfhi(v.z); o[6] += wp * bflo(v.w); o[7] += wp * bfhi(v.w);
;         }
;         u32x4 ov; ov.x = pk2(o[0], o[1]); ov.y = pk2(o[2], o[3]); ov.z = pk2(o[4], o[5]); ov.w = pk2(o[6], o[7]);
;         *(u32x4*)(CAT + (size_t)t * 2048 + c) = ov;
.Lcmb_loop:
	s_cmp_eq_u32 s0, 1
	s_cbranch_scc1 .Lcmb_lastA
	v_min_i32_e32 v156, s1, v2
	v_ashrrev_i32_e32 v155, 7, v156
	v_lshrrev_b32_e32 v157, 1, v156
	v_and_b32_e32 v157, 56, v157
	v_lshl_or_b32 v157, v155, 6, v157
	global_load_dwordx2 v[136:137], v157, s[26:27]
	global_load_dwordx2 v[138:139], v157, s[6:7]
	global_load_dwordx2 v[140:141], v157, s[8:9]
	v_and_b32_e32 v154, 0x7f, v156
	v_lshlrev_b32_e32 v156, 4, v156
	v_lshlrev_b32_e32 v154, 4, v154
	global_load_dwordx4 v[142:145], v156, s[16:17]
	v_lshl_or_b32 v154, v155, 12, v154
	global_load_dwordx4 v[146:149], v156, s[20:21]
	global_load_dwordx4 v[150:153], v156, s[22:23]
	v_add_u32_e32 v180, 512, v2
	v_min_i32_e32 v180, s1, v180
	v_ashrrev_i32_e32 v179, 7, v180
	v_lshrrev_b32_e32 v181, 1, v180
	v_and_b32_e32 v181, 56, v181
	v_lshl_or_b32 v181, v179, 6, v181
	global_load_dwordx2 v[160:161], v181, s[26:27]
	global_load_dwordx2 v[162:163], v181, s[6:7]
	global_load_dwordx2 v[164:165], v181, s[8:9]
	v_and_b32_e32 v178, 0x7f, v180
	v_lshlrev_b32_e32 v180, 4, v180
	v_lshlrev_b32_e32 v178, 4, v178
	global_load_dwordx4 v[166:169], v180, s[16:17]
	v_lshl_or_b32 v178, v179, 12, v178
	global_load_dwordx4 v[170:173], v180, s[20:21]
	global_load_dwordx4 v[174:177], v180, s[22:23]
	v_add_u32_e32 v208, 1024, v2
	v_min_i32_e32 v208, s1, v208
	v_ashrrev_i32_e32 v207, 7, v208
	v_lshrrev_b32_e32 v209, 1, v208
	v_and_b32_e32 v209, 56, v209
	v_lshl_or_b32 v209, v207, 6, v209
	global_load_dwordx2 v[188:189], v209, s[26:27]
	global_load_dwordx2 v[190:191], v209, s[6:7]
	global_load_dwordx2 v[192:193], v209, s[8:9]
	v_and_b32_e32 v206, 0x7f, v208
	v_lshlrev_b32_e32 v208, 4, v208
	v_lshlrev_b32_e32 v206, 4, v206
	global_load_dwordx4 v[194:197], v208, s[16:17]
	v_lshl_or_b32 v206, v207, 12, v206
	global_load_dwordx4 v[198:201], v208, s[20:21]
	global_load_dwordx4 v[202:205], v208, s[22:23]
	v_add_u32_e32 v232, 1536, v2
	v_min_i32_e32 v232, s1, v232
	v_ashrrev_i32_e32 v231, 7, v232
	v_lshrrev_b32_e32 v233, 1, v232
	v_and_b32_e32 v233, 56, v233
	v_lshl_or_b32 v233, v231, 6, v233
	global_load_dwordx2 v[212:213], v233, s[26:27]
	global_load_dwordx2 v[214:215], v233, s[6:7]
	global_load_dwordx2 v[216:217], v233, s[8:9]
	v_and_b32_e32 v230, 0x7f, v232
	v_lshlrev_b32_e32 v232, 4, v232
	v_lshlrev_b32_e32 v230, 4, v230
	global_load_dwordx4 v[218:221], v232, s[16:17]
	v_lshl_or_b32 v230, v231, 12, v230
	global_load_dwordx4 v[222:225], v232, s[20:21]
	global_load_dwordx4 v[226:229], v232, s[22:23]
	v_add_u32_e32 v2, 2048, v2
	s_waitcnt vmcnt(42)
	v_max3_f32 v0, v40, v42, v44
	v_sub_f32_e32 v18, v40, v0
	v_sub_f32_e32 v36, v42, v0
	v_sub_f32_e32 v0, v44, v0
	v_cmp_gt_f32_e32 vcc, s19, v18
	v_cmp_gt_f32_e64 s[4:5], s19, v36
	v_cmp_gt_f32_e64 s[32:33], s19, v0
	v_cndmask_b32_e32 v37, 0, v4, vcc
	v_cndmask_b32_e64 v38, 0, v4, s[4:5]
	v_cndmask_b32_e64 v39, 0, v4, s[32:33]
	v_add_f32_e32 v18, v18, v37
	v_add_f32_e32 v36, v36, v38
	v_add_f32_e32 v0, v0, v39
	v_exp_f32_e32 v18, v18
	v_exp_f32_e32 v36, v36
	v_exp_f32_e32 v0, v0
	v_cndmask_b32_e32 v37, 0, v5, vcc
	v_cndmask_b32_e64 v38, 0, v5, s[4:5]
	v_cndmask_b32_e64 v39, 0, v5, s[32:33]
	v_mov_b32_e32 v20, v45
	v_mov_b32_e32 v21, v43
	v_ldexp_f32 v18, v18, v37
	v_ldexp_f32 v37, v36, v38
	v_ldexp_f32 v36, v0, v39
	v_mul_f32_e32 v0, v41, v18
	v_fma_f32 v38, v41, v18, 0
	v_pk_mul_f32 v[18:19], v[20:21], v[36:37]
	v_add_f32_e32 v20, v19, v38
	v_add_f32_e32 v20, v18, v20
	v_div_scale_f32 v21, s[4:5], v20, v20, 1.0
	v_rcp_f32_e32 v37, v21
	v_div_scale_f32 v36, vcc, 1.0, v20, 1.0
	v_fma_f32 v38, -v21, v37, 1.0
	v_fmac_f32_e32 v37, v38, v37
	v_mul_f32_e32 v38, v36, v37
	v_fma_f32 v39, -v21, v38, v36
	v_fmac_f32_e32 v38, v39, v37
	v_fma_f32 v21, -v21, v38, v36
	v_div_fmas_f32 v21, v21, v37, v38
	v_div_fixup_f32 v21, v21, v20, 1.0
	v_mul_f32_e32 v0, v0, v21
	v_mul_f32_e32 v20, v19, v21
	v_mul_f32_e32 v18, v18, v21
	v_lshlrev_b32_e32 v22, 16, v46
	v_and_b32_e32 v23, 0xffff0000, v46
	v_lshlrev_b32_e32 v6, 16, v47
	v_and_b32_e32 v7, 0xffff0000, v47
	v_lshlrev_b32_e32 v30, 16, v48
	v_and_b32_e32 v31, 0xffff0000, v48
	v_lshlrev_b32_e32 v8, 16, v49
	v_and_b32_e32 v9, 0xffff0000, v49
	v_lshlrev_b32_e32 v26, 16, v50
	v_and_b32_e32 v27, 0xffff0000, v50
	v_lshlrev_b32_e32 v10, 16, v51
	v_and_b32_e32 v11, 0xffff0000, v51
	v_lshlrev_b32_e32 v32, 16, v52
	v_and_b32_e32 v33, 0xffff0000, v52
	v_lshlrev_b32_e32 v12, 16, v53
	v_and_b32_e32 v13, 0xffff0000, v53
	v_pk_fma_f32 v[22:23], v[0:1], v[22:23], 0 op_sel_hi:[0,1,0]
	v_pk_fma_f32 v[6:7], v[0:1], v[6:7], 0 op_sel_hi:[0,1,0]
	v_pk_fma_f32 v[30:31], v[0:1], v[30:31], 0 op_sel_hi:[0,1,0]
	v_pk_fma_f32 v[8:9], v[0:1], v[8:9], 0 op_sel_hi:[0,1,0]
	v_lshlrev_b32_e32 v28, 16, v54
	v_and_b32_e32 v29, 0xffff0000, v54
	v_lshlrev_b32_e32 v14, 16, v55
	v_and_b32_e32 v15, 0xffff0000, v55
	v_lshlrev_b32_e32 v34, 16, v56
	v_and_b32_e32 v35, 0xffff0000, v56
	v_lshlrev_b32_e32 v16, 16, v57
	v_and_b32_e32 v17, 0xffff0000, v57
	v_pk_fma_f32 v[22:23], v[20:21], v[26:27], v[22:23] op_sel_hi:[0,1,1]
	v_pk_fma_f32 v[6:7], v[20:21], v[10:11], v[6:7] op_sel_hi:[0,1,1]
	v_pk_fma_f32 v[10:11], v[20:21], v[32:33], v[30:31] op_sel_hi:[0,1,1]
	v_pk_fma_f32 v[8:9], v[20:21], v[12:13], v[8:9] op_sel_hi:[0,1,1]
	v_pk_fma_f32 v[12:13], v[18:19], v[28:29], v[22:23] op_sel_hi:[0,1,1]
	v_pk_fma_f32 v[14:15], v[18:19], v[14:15], v[6:7] op_sel_hi:[0,1,1]
	v_pk_fma_f32 v[10:11], v[18:19], v[34:35], v[10:11] op_sel_hi:[0,1,1]
	v_pk_fma_f32 v[16:17], v[18:19], v[16:17], v[8:9] op_sel_hi:[0,1,1]
	v_cvt_pk_bf16_f32 v46, v12, v13
	v_cvt_pk_bf16_f32 v47, v14, v15
	v_cvt_pk_bf16_f32 v48, v10, v11
	v_cvt_pk_bf16_f32 v49, v16, v17
	global_store_dwordx4 v58, v[46:49], s[10:11]
	s_waitcnt vmcnt(37)
; __device__ __forceinline__ unsigned pk2(float lo, float hi) { f32x2_t v = {lo, hi}; bf16x2_t b = __builtin_convertvector(v, bf16x2_t); return __builtin_bit_cast(unsigned, b); }
; __device__ __forceinline__ float bflo(unsigned w) { return __uint_as_float(w << 16); }
; __device__ __forceinline__ float bfhi(unsigned w) { return __uint_as_float(w & 0xffff0000u); }
; __device__ __forceinline__ bf16* po_base(unsigned char* ws, int pat) { return (bf16*)(ws + (pat < 2 ? 436 * MiB + (size_t)pat * 32 * MiB : WS_Y)); }
; __device__ __forceinline__ void attn_combine(unsigned char* ws, const float* __restrict__ PM, bf16* CAT, int gtid, int gthreads, int iend = S * 128) {
;     for (int idx = gtid; idx < iend; idx += gthreads) {
;         const int t = idx >> 7, c = (idx & 127) * 8, hh = c >> 7;
;         float mm[3], ll[3];
; #pragma unroll
;         for (int p = 0; p < 3; ++p) { const f32x2_t ml = *(const f32x2_t*)(PM + (((size_t)p * S + t) * 8 + hh) * 2); mm[p] = ml[0]; ll[p] = ml[1]; }
;         const float ma = fmaxf(mm[0], fmaxf(mm[1], mm[2]));
;         float w[3], den = 0.f;
; #pragma unroll
;         for (int p = 0; p < 3; ++p) { w[p] = exp2f(mm[p] - ma) * ll[p]; den += w[p]; }
;         const float inv = 1.f / den;
;         float o[8] = {0.f, 0.f, 0.f, 0.f, 0.f, 0.f, 0.f, 0.f};
; #pragma unroll
;         for (int p = 0; p < 3; ++p) {
;             const u32x4 v = *(const u32x4*)(po_base(ws, p) + (size_t)t * 1024 + c); const float wp = w[p] * inv;
;             o[0] += wp * bflo(v.x); o[1] += wp * bfhi(v.x); o[2] += wp * bflo(v.y); o[3] += wp * bfhi(v.y); o[4] += wp * bflo(v.z); o[5] += wp * bfhi(v.z); o[6] += wp * bflo(v.w); o[7] += wp * bfhi(v.w);
;         }
;         u32x4 ov; ov.x = pk2(o[0], o[1]); ov.y = pk2(o[2], o[3]); ov.z = pk2(o[4], o[5]); ov.w = pk2(o[6], o[7]);
;         *(u32x4*)(CAT + (size_t)t * 2048 + c) = ov;
	v_max3_f32 v0, v64, v66, v68
	v_sub_f32_e32 v18, v64, v0
	v_sub_f32_e32 v36, v66, v0
	v_sub_f32_e32 v0, v68, v0
	v_cmp_gt_f32_e32 vcc, s19, v18
	v_cmp_gt_f32_e64 s[4:5], s19, v36
	v_cmp_gt_f32_e64 s[32:33], s19, v0
	v_cndmask_b32_e32 v37, 0, v4, vcc
	v_cndmask_b32_e64 v38, 0, v4, s[4:5]
	v_cndmask_b32_e64 v39, 0, v4, s[32:33]
	v_add_f32_e32 v18, v18, v37
	v_add_f32_e32 v36, v36, v38
	v_add_f32_e32 v0, v0, v39
	v_exp_f32_e32 v18, v18
	v_exp_f32_e32 v36, v36
	v_exp_f32_e32 v0, v0
	v_cndmask_b32_e32 v37, 0, v5, vcc
	v_cndmask_b32_e64 v38, 0, v5, s[4:5]
	v_cndmask_b32_e64 v39, 0, v5, s[32:33]
	v_mov_b32_e32 v20, v69
	v_mov_b32_e32 v21, v67
	v_ldexp_f32 v18, v18, v37
	v_ldexp_f32 v37, v36, v38
	v_ldexp_f32 v36, v0, v39
	v_mul_f32_e32 v0, v65, v18
	v_fma_f32 v38, v65, v18, 0
	v_pk_mul_f32 v[18:19], v[20:21], v[36:37]
	v_add_f32_e32 v20, v19, v38
	v_add_f32_e32 v20, v18, v20
	v_div_scale_f32 v21, s[4:5], v20, v20, 1.0
	v_rcp_f32_e32 v37, v21
	v_div_scale_f32 v36, vcc, 1.0, v20, 1.0
	v_fma_f32 v38, -v21, v37, 1.0
	v_fmac_f32_e32 v37, v38, v37
	v_mul_f32_e32 v38, v36, v37
	v_fma_f32 v39, -v21, v38, v36
	v_fmac_f32_e32 v38, v39, v37
	v_fma_f32 v21, -v21, v38, v36
	v_div_fmas_f32 v21, v21, v37, v38
	v_div_fixup_f32 v21, v21, v20, 1.0
	v_mul_f32_e32 v0, v0, v21
	v_mul_f32_e32 v20, v19, v21
	v_mul_f32_e32 v18, v18, v21
	v_lshlrev_b32_e32 v22, 16, v70
	v_and_b32_e32 v23, 0xffff0000, v70
	v_lshlrev_b32_e32 v6, 16, v71
	v_and_b32_e32 v7, 0xffff0000, v71
	v_lshlrev_b32_e32 v30, 16, v72
	v_and_b32_e32 v31, 0xffff0000, v72
	v_lshlrev_b32_e32 v8, 16, v73
	v_and_b32_e32 v9, 0xffff0000, v73
	v_lshlrev_b32_e32 v26, 16, v74
	v_and_b32_e32 v27, 0xffff0000, v74
	v_lshlrev_b32_e32 v10, 16, v75
	v_and_b32_e32 v11, 0xffff0000, v75
	v_lshlrev_b32_e32 v32, 16, v76
	v_and_b32_e32 v33, 0xffff0000, v76
	v_lshlrev_b32_e32 v12, 16, v77
	v_and_b32_e32 v13, 0xffff0000, v77
	v_pk_fma_f32 v[22:23], v[0:1], v[22:23], 0 op_sel_hi:[0,1,0]
	v_pk_fma_f32 v[6:7], v[0:1], v[6:7], 0 op_sel_hi:[0,1,0]
	v_pk_fma_f32 v[30:31], v[0:1], v[30:31], 0 op_sel_hi:[0,1,0]
	v_pk_fma_f32 v[8:9], v[0:1], v[8:9], 0 op_sel_hi:[0,1,0]
	v_lshlrev_b32_e32 v28, 16, v78
	v_and_b32_e32 v29, 0xffff0000, v78
	v_lshlrev_b32_e32 v14, 16, v79
	v_and_b32_e32 v15, 0xffff0000, v79
	v_lshlrev_b32_e32 v34, 16, v80
	v_and_b32_e32 v35, 0xffff0000, v80
	v_lshlrev_b32_e32 v16, 16, v81
	v_and_b32_e32 v17, 0xffff0000, v81
	v_pk_fma_f32 v[22:23], v[20:21], v[26:27], v[22:23] op_sel_hi:[0,1,1]
	v_pk_fma_f32 v[6:7], v[20:21], v[10:11], v[6:7] op_sel_hi:[0,1,1]
	v_pk_fma_f32 v[10:11], v[20:21], v[32:33], v[30:31] op_sel_hi:[0,1,1]
	v_pk_fma_f32 v[8:9], v[20:21], v[12:13], v[8:9] op_sel_hi:[0,1,1]
	v_pk_fma_f32 v[12:13], v[18:19], v[28:29], v[22:23] op_sel_hi:[0,1,1]
	v_pk_fma_f32 v[14:15], v[18:19], v[14:15], v[6:7] op_sel_hi:[0,1,1]
	v_pk_fma_f32 v[10:11], v[18:19], v[34:35], v[10:11] op_sel_hi:[0,1,1]
	v_pk_fma_f32 v[16:17], v[18:19], v[16:17], v[8:9] op_sel_hi:[0,1,1]
	v_cvt_pk_bf16_f32 v70, v12, v13
	v_cvt_pk_bf16_f32 v71, v14, v15
	v_cvt_pk_bf16_f32 v72, v10, v11
	v_cvt_pk_bf16_f32 v73, v16, v17
	global_store_dwordx4 v82, v[70:73], s[10:11]
	s_waitcnt vmcnt(32)
	v_max3_f32 v0, v88, v90, v92
	v_sub_f32_e32 v18, v88, v0
	v_sub_f32_e32 v36, v90, v0
	v_sub_f32_e32 v0, v92, v0
	v_cmp_gt_f32_e32 vcc, s19, v18
	v_cmp_gt_f32_e64 s[4:5], s19, v36
	v_cmp_gt_f32_e64 s[32:33], s19, v0
	v_cndmask_b32_e32 v37, 0, v4, vcc
	v_cndmask_b32_e64 v38, 0, v4, s[4:5]
	v_cndmask_b32_e64 v39, 0, v4, s[32:33]
	v_add_f32_e32 v18, v18, v37
	v_add_f32_e32 v36, v36, v38
	v_add_f32_e32 v0, v0, v39
	v_exp_f32_e32 v18, v18
	v_exp_f32_e32 v36, v36
	v_exp_f32_e32 v0, v0
	v_cndmask_b32_e32 v37, 0, v5, vcc
	v_cndmask_b32_e64 v38, 0, v5, s[4:5]
	v_cndmask_b32_e64 v39, 0, v5, s[32:33]
	v_mov_b32_e32 v20, v93
	v_mov_b32_e32 v21, v91
	v_ldexp_f32 v18, v18, v37
	v_ldexp_f32 v37, v36, v38
	v_ldexp_f32 v36, v0, v39
	v_mul_f32_e32 v0, v89, v18
	v_fma_f32 v38, v89, v18, 0
	v_pk_mul_f32 v[18:19], v[20:21], v[36:37]
	v_add_f32_e32 v20, v19, v38
	v_add_f32_e32 v20, v18, v20
	v_div_scale_f32 v21, s[4:5], v20, v20, 1.0
	v_rcp_f32_e32 v37, v21
	v_div_scale_f32 v36, vcc, 1.0, v20, 1.0
	v_fma_f32 v38, -v21, v37, 1.0
	v_fmac_f32_e32 v37, v38, v37
	v_mul_f32_e32 v38, v36, v37
	v_fma_f32 v39, -v21, v38, v36
	v_fmac_f32_e32 v38, v39, v37
	v_fma_f32 v21, -v21, v38, v36
	v_div_fmas_f32 v21, v21, v37, v38
	v_div_fixup_f32 v21, v21, v20, 1.0
	v_mul_f32_e32 v0, v0, v21
	v_mul_f32_e32 v20, v19, v21
	v_mul_f32_e32 v18, v18, v21
	v_lshlrev_b32_e32 v22, 16, v94
	v_and_b32_e32 v23, 0xffff0000, v94
	v_lshlrev_b32_e32 v6, 16, v95
	v_and_b32_e32 v7, 0xffff0000, v95
	v_lshlrev_b32_e32 v30, 16, v96
	v_and_b32_e32 v31, 0xffff0000, v96
	v_lshlrev_b32_e32 v8, 16, v97
	v_and_b32_e32 v9, 0xffff0000, v97
	v_lshlrev_b32_e32 v26, 16, v98
	v_and_b32_e32 v27, 0xffff0000, v98
	v_lshlrev_b32_e32 v10, 16, v99
	v_and_b32_e32 v11, 0xffff0000, v99
	v_lshlrev_b32_e32 v32, 16, v100
	v_and_b32_e32 v33, 0xffff0000, v100
	v_lshlrev_b32_e32 v12, 16, v101
	v_and_b32_e32 v13, 0xffff0000, v101
	v_pk_fma_f32 v[22:23], v[0:1], v[22:23], 0 op_sel_hi:[0,1,0]
	v_pk_fma_f32 v[6:7], v[0:1], v[6:7], 0 op_sel_hi:[0,1,0]
	v_pk_fma_f32 v[30:31], v[0:1], v[30:31], 0 op_sel_hi:[0,1,0]
	v_pk_fma_f32 v[8:9], v[0:1], v[8:9], 0 op_sel_hi:[0,1,0]
	v_lshlrev_b32_e32 v28, 16, v102
	v_and_b32_e32 v29, 0xffff0000, v102
	v_lshlrev_b32_e32 v14, 16, v103
	v_and_b32_e32 v15, 0xffff0000, v103
	v_lshlrev_b32_e32 v34, 16, v104
	v_and_b32_e32 v35, 0xffff0000, v104
	v_lshlrev_b32_e32 v16, 16, v105
	v_and_b32_e32 v17, 0xffff0000, v105
	v_pk_fma_f32 v[22:23], v[20:21], v[26:27], v[22:23] op_sel_hi:[0,1,1]
	v_pk_fma_f32 v[6:7], v[20:21], v[10:11], v[6:7] op_sel_hi:[0,1,1]
	v_pk_fma_f32 v[10:11], v[20:21], v[32:33], v[30:31] op_sel_hi:[0,1,1]
	v_pk_fma_f32 v[8:9], v[20:21], v[12:13], v[8:9] op_sel_hi:[0,1,1]
	v_pk_fma_f32 v[12:13], v[18:19], v[28:29], v[22:23] op_sel_hi:[0,1,1]
	v_pk_fma_f32 v[14:15], v[18:19], v[14:15], v[6:7] op_sel_hi:[0,1,1]
	v_pk_fma_f32 v[10:11], v[18:19], v[34:35], v[10:11] op_sel_hi:[0,1,1]
	v_pk_fma_f32 v[16:17], v[18:19], v[16:17], v[8:9] op_sel_hi:[0,1,1]
	v_cvt_pk_bf16_f32 v94, v12, v13
	v_cvt_pk_bf16_f32 v95, v14, v15
	v_cvt_pk_bf16_f32 v96, v10, v11
	v_cvt_pk_bf16_f32 v97, v16, v17
	global_store_dwordx4 v106, v[94:97], s[10:11]
	s_waitcnt vmcnt(27)
; __device__ __forceinline__ unsigned pk2(float lo, float hi) { f32x2_t v = {lo, hi}; bf16x2_t b = __builtin_convertvector(v, bf16x2_t); return __builtin_bit_cast(unsigned, b); }
; __device__ __forceinline__ float bflo(unsigned w) { return __uint_as_float(w << 16); }
; __device__ __forceinline__ float bfhi(unsigned w) { return __uint_as_float(w & 0xffff0000u); }
; __device__ __forceinline__ bf16* po_base(unsigned char* ws, int pat) { return (bf16*)(ws + (pat < 2 ? 436 * MiB + (size_t)pat * 32 * MiB : WS_Y)); }
; __device__ __forceinline__ void attn_combine(unsigned char* ws, const float* __restrict__ PM, bf16* CAT, int gtid, int gthreads, int iend = S * 128) {
;     for (int idx = gtid; idx < iend; idx += gthreads) {
;         const int t = idx >> 7, c = (idx & 127) * 8, hh = c >> 7;
;         float mm[3], ll[3];
; #pragma unroll
;         for (int p = 0; p < 3; ++p) { const f32x2_t ml = *(const f32x2_t*)(PM + (((size_t)p * S + t) * 8 + hh) * 2); mm[p] = ml[0]; ll[p] = ml[1]; }
;         const float ma = fmaxf(mm[0], fmaxf(mm[1], mm[2]));
;         float w[3], den = 0.f;
; #pragma unroll
;         for (int p = 0; p < 3; ++p) { w[p] = exp2f(mm[p] - ma) * ll[p]; den += w[p]; }
;         const float inv = 1.f / den;
;         float o[8] = {0.f, 0.f, 0.f, 0.f, 0.f, 0.f, 0.f, 0.f};
; #pragma unroll
;         for (int p = 0; p < 3; ++p) {
;             const u32x4 v = *(const u32x4*)(po_base(ws, p) + (size_t)t * 1024 + c); const float wp = w[p] * inv;
;             o[0] += wp * bflo(v.x); o[1] += wp * bfhi(v.x); o[2] += wp * bflo(v.y); o[3] += wp * bfhi(v.y); o[4] += wp * bflo(v.z); o[5] += wp * bfhi(v.z); o[6] += wp * bflo(v.w); o[7] += wp * bfhi(v.w);
;         }
;         u32x4 ov; ov.x = pk2(o[0], o[1]); ov.y = pk2(o[2], o[3]); ov.z = pk2(o[4], o[5]); ov.w = pk2(o[6], o[7]);
;         *(u32x4*)(CAT + (size_t)t * 2048 + c) = ov;
	v_max3_f32 v0, v112, v114, v116
	v_sub_f32_e32 v18, v112, v0
	v_sub_f32_e32 v36, v114, v0
	v_sub_f32_e32 v0, v116, v0
	v_cmp_gt_f32_e32 vcc, s19, v18
	v_cmp_gt_f32_e64 s[4:5], s19, v36
	v_cmp_gt_f32_e64 s[32:33], s19, v0
	v_cndmask_b32_e32 v37, 0, v4, vcc
	v_cndmask_b32_e64 v38, 0, v4, s[4:5]
	v_cndmask_b32_e64 v39, 0, v4, s[32:33]
	v_add_f32_e32 v18, v18, v37
	v_add_f32_e32 v36, v36, v38
	v_add_f32_e32 v0, v0, v39
	v_exp_f32_e32 v18, v18
	v_exp_f32_e32 v36, v36
	v_exp_f32_e32 v0, v0
	v_cndmask_b32_e32 v37, 0, v5, vcc
	v_cndmask_b32_e64 v38, 0, v5, s[4:5]
	v_cndmask_b32_e64 v39, 0, v5, s[32:33]
	v_mov_b32_e32 v20, v117
	v_mov_b32_e32 v21, v115
	v_ldexp_f32 v18, v18, v37
	v_ldexp_f32 v37, v36, v38
	v_ldexp_f32 v36, v0, v39
	v_mul_f32_e32 v0, v113, v18
	v_fma_f32 v38, v113, v18, 0
	v_pk_mul_f32 v[18:19], v[20:21], v[36:37]
	v_add_f32_e32 v20, v19, v38
	v_add_f32_e32 v20, v18, v20
	v_div_scale_f32 v21, s[4:5], v20, v20, 1.0
	v_rcp_f32_e32 v37, v21
	v_div_scale_f32 v36, vcc, 1.0, v20, 1.0
	v_fma_f32 v38, -v21, v37, 1.0
	v_fmac_f32_e32 v37, v38, v37
	v_mul_f32_e32 v38, v36, v37
	v_fma_f32 v39, -v21, v38, v36
	v_fmac_f32_e32 v38, v39, v37
	v_fma_f32 v21, -v21, v38, v36
	v_div_fmas_f32 v21, v21, v37, v38
	v_div_fixup_f32 v21, v21, v20, 1.0
	v_mul_f32_e32 v0, v0, v21
	v_mul_f32_e32 v20, v19, v21
	v_mul_f32_e32 v18, v18, v21
	v_lshlrev_b32_e32 v22, 16, v118
	v_and_b32_e32 v23, 0xffff0000, v118
	v_lshlrev_b32_e32 v6, 16, v119
	v_and_b32_e32 v7, 0xffff0000, v119
	v_lshlrev_b32_e32 v30, 16, v120
	v_and_b32_e32 v31, 0xffff0000, v120
	v_lshlrev_b32_e32 v8, 16, v121
	v_and_b32_e32 v9, 0xffff0000, v121
	v_lshlrev_b32_e32 v26, 16, v122
	v_and_b32_e32 v27, 0xffff0000, v122
	v_lshlrev_b32_e32 v10, 16, v123
	v_and_b32_e32 v11, 0xffff0000, v123
	v_lshlrev_b32_e32 v32, 16, v124
	v_and_b32_e32 v33, 0xffff0000, v124
	v_lshlrev_b32_e32 v12, 16, v125
	v_and_b32_e32 v13, 0xffff0000, v125
	v_pk_fma_f32 v[22:23], v[0:1], v[22:23], 0 op_sel_hi:[0,1,0]
	v_pk_fma_f32 v[6:7], v[0:1], v[6:7], 0 op_sel_hi:[0,1,0]
	v_pk_fma_f32 v[30:31], v[0:1], v[30:31], 0 op_sel_hi:[0,1,0]
	v_pk_fma_f32 v[8:9], v[0:1], v[8:9], 0 op_sel_hi:[0,1,0]
	v_lshlrev_b32_e32 v28, 16, v126
	v_and_b32_e32 v29, 0xffff0000, v126
	v_lshlrev_b32_e32 v14, 16, v127
	v_and_b32_e32 v15, 0xffff0000, v127
	v_lshlrev_b32_e32 v34, 16, v128
	v_and_b32_e32 v35, 0xffff0000, v128
	v_lshlrev_b32_e32 v16, 16, v129
	v_and_b32_e32 v17, 0xffff0000, v129
	v_pk_fma_f32 v[22:23], v[20:21], v[26:27], v[22:23] op_sel_hi:[0,1,1]
	v_pk_fma_f32 v[6:7], v[20:21], v[10:11], v[6:7] op_sel_hi:[0,1,1]
	v_pk_fma_f32 v[10:11], v[20:21], v[32:33], v[30:31] op_sel_hi:[0,1,1]
	v_pk_fma_f32 v[8:9], v[20:21], v[12:13], v[8:9] op_sel_hi:[0,1,1]
	v_pk_fma_f32 v[12:13], v[18:19], v[28:29], v[22:23] op_sel_hi:[0,1,1]
	v_pk_fma_f32 v[14:15], v[18:19], v[14:15], v[6:7] op_sel_hi:[0,1,1]
	v_pk_fma_f32 v[10:11], v[18:19], v[34:35], v[10:11] op_sel_hi:[0,1,1]
	v_pk_fma_f32 v[16:17], v[18:19], v[16:17], v[8:9] op_sel_hi:[0,1,1]
	v_cvt_pk_bf16_f32 v118, v12, v13
	v_cvt_pk_bf16_f32 v119, v14, v15
	v_cvt_pk_bf16_f32 v120, v10, v11
	v_cvt_pk_bf16_f32 v121, v16, v17
	global_store_dwordx4 v130, v[118:121], s[10:11]
	s_add_i32 s0, s0, -1
	s_cmp_eq_u32 s0, 1
	s_cbranch_scc1 .Lcmb_lastB
	v_min_i32_e32 v60, s1, v2
	v_ashrrev_i32_e32 v59, 7, v60
	v_lshrrev_b32_e32 v61, 1, v60
	v_and_b32_e32 v61, 56, v61
	v_lshl_or_b32 v61, v59, 6, v61
	global_load_dwordx2 v[40:41], v61, s[26:27]
	global_load_dwordx2 v[42:43], v61, s[6:7]
	global_load_dwordx2 v[44:45], v61, s[8:9]
	v_and_b32_e32 v58, 0x7f, v60
	v_lshlrev_b32_e32 v60, 4, v60
	v_lshlrev_b32_e32 v58, 4, v58
	global_load_dwordx4 v[46:49], v60, s[16:17]
	v_lshl_or_b32 v58, v59, 12, v58
	global_load_dwordx4 v[50:53], v60, s[20:21]
	global_load_dwordx4 v[54:57], v60, s[22:23]
	v_add_u32_e32 v84, 512, v2
	v_min_i32_e32 v84, s1, v84
	v_ashrrev_i32_e32 v83, 7, v84
	v_lshrrev_b32_e32 v85, 1, v84
	v_and_b32_e32 v85, 56, v85
	v_lshl_or_b32 v85, v83, 6, v85
	global_load_dwordx2 v[64:65], v85, s[26:27]
	global_load_dwordx2 v[66:67], v85, s[6:7]
	global_load_dwordx2 v[68:69], v85, s[8:9]
	v_and_b32_e32 v82, 0x7f, v84
	v_lshlrev_b32_e32 v84, 4, v84
	v_lshlrev_b32_e32 v82, 4, v82
	global_load_dwordx4 v[70:73], v84, s[16:17]
	v_lshl_or_b32 v82, v83, 12, v82
	global_load_dwordx4 v[74:77], v84, s[20:21]
	global_load_dwordx4 v[78:81], v84, s[22:23]
	v_add_u32_e32 v108, 1024, v2
	v_min_i32_e32 v108, s1, v108
	v_ashrrev_i32_e32 v107, 7, v108
	v_lshrrev_b32_e32 v109, 1, v108
	v_and_b32_e32 v109, 56, v109
	v_lshl_or_b32 v109, v107, 6, v109
	global_load_dwordx2 v[88:89], v109, s[26:27]
	global_load_dwordx2 v[90:91], v109, s[6:7]
	global_load_dwordx2 v[92:93], v109, s[8:9]
	v_and_b32_e32 v106, 0x7f, v108
	v_lshlrev_b32_e32 v108, 4, v108
	v_lshlrev_b32_e32 v106, 4, v106
	global_load_dwordx4 v[94:97], v108, s[16:17]
	v_lshl_or_b32 v106, v107, 12, v106
	global_load_dwordx4 v[98:101], v108, s[20:21]
	global_load_dwordx4 v[102:105], v108, s[22:23]
	v_add_u32_e32 v132, 1536, v2
	v_min_i32_e32 v132, s1, v132
	v_ashrrev_i32_e32 v131, 7, v132
	v_lshrrev_b32_e32 v133, 1, v132
	v_and_b32_e32 v133, 56, v133
	v_lshl_or_b32 v133, v131, 6, v133
	global_load_dwordx2 v[112:113], v133, s[26:27]
	global_load_dwordx2 v[114:115], v133, s[6:7]
	global_load_dwordx2 v[116:117], v133, s[8:9]
	v_and_b32_e32 v130, 0x7f, v132
	v_lshlrev_b32_e32 v132, 4, v132
	v_lshlrev_b32_e32 v130, 4, v130
	global_load_dwordx4 v[118:121], v132, s[16:17]
	v_lshl_or_b32 v130, v131, 12, v130
	global_load_dwordx4 v[122:125], v132, s[20:21]
	global_load_dwordx4 v[126:129], v132, s[22:23]
	v_add_u32_e32 v2, 2048, v2
	s_waitcnt vmcnt(42)
; __device__ __forceinline__ unsigned pk2(float lo, float hi) { f32x2_t v = {lo, hi}; bf16x2_t b = __builtin_convertvector(v, bf16x2_t); return __builtin_bit_cast(unsigned, b); }
; __device__ __forceinline__ float bflo(unsigned w) { return __uint_as_float(w << 16); }
; __device__ __forceinline__ float bfhi(unsigned w) { return __uint_as_float(w & 0xffff0000u); }
; __device__ __forceinline__ bf16* po_base(unsigned char* ws, int pat) { return (bf16*)(ws + (pat < 2 ? 436 * MiB + (size_t)pat * 32 * MiB : WS_Y)); }
; __device__ __forceinline__ void attn_combine(unsigned char* ws, const float* __restrict__ PM, bf16* CAT, int gtid, int gthreads, int iend = S * 128) {
;     for (int idx = gtid; idx < iend; idx += gthreads) {
;         const int t = idx >> 7, c = (idx & 127) * 8, hh = c >> 7;
;         float mm[3], ll[3];
; #pragma unroll
;         for (int p = 0; p < 3; ++p) { const f32x2_t ml = *(const f32x2_t*)(PM + (((size_t)p * S + t) * 8 + hh) * 2); mm[p] = ml[0]; ll[p] = ml[1]; }
;         const float ma = fmaxf(mm[0], fmaxf(mm[1], mm[2]));
;         float w[3], den = 0.f;
; #pragma unroll
;         for (int p = 0; p < 3; ++p) { w[p] = exp2f(mm[p] - ma) * ll[p]; den += w[p]; }
;         const float inv = 1.f / den;
;         float o[8] = {0.f, 0.f, 0.f, 0.f, 0.f, 0.f, 0.f, 0.f};
; #pragma unroll
;         for (int p = 0; p < 3; ++p) {
;             const u32x4 v = *(const u32x4*)(po_base(ws, p) + (size_t)t * 1024 + c); const float wp = w[p] * inv;
;             o[0] += wp * bflo(v.x); o[1] += wp * bfhi(v.x); o[2] += wp * bflo(v.y); o[3] += wp * bfhi(v.y); o[4] += wp * bflo(v.z); o[5] += wp * bfhi(v.z); o[6] += wp * bflo(v.w); o[7] += wp * bfhi(v.w);
;         }
;         u32x4 ov; ov.x = pk2(o[0], o[1]); ov.y = pk2(o[2], o[3]); ov.z = pk2(o[4], o[5]); ov.w = pk2(o[6], o[7]);
;         *(u32x4*)(CAT + (size_t)t * 2048 + c) = ov;
	v_max3_f32 v0, v136, v138, v140
	v_sub_f32_e32 v18, v136, v0
	v_sub_f32_e32 v36, v138, v0
	v_sub_f32_e32 v0, v140, v0
	v_cmp_gt_f32_e32 vcc, s19, v18
	v_cmp_gt_f32_e64 s[4:5], s19, v36
	v_cmp_gt_f32_e64 s[32:33], s19, v0
	v_cndmask_b32_e32 v37, 0, v4, vcc
	v_cndmask_b32_e64 v38, 0, v4, s[4:5]
	v_cndmask_b32_e64 v39, 0, v4, s[32:33]
	v_add_f32_e32 v18, v18, v37
	v_add_f32_e32 v36, v36, v38
	v_add_f32_e32 v0, v0, v39
	v_exp_f32_e32 v18, v18
	v_exp_f32_e32 v36, v36
	v_exp_f32_e32 v0, v0
	v_cndmask_b32_e32 v37, 0, v5, vcc
	v_cndmask_b32_e64 v38, 0, v5, s[4:5]
	v_cndmask_b32_e64 v39, 0, v5, s[32:33]
	v_mov_b32_e32 v20, v141
	v_mov_b32_e32 v21, v139
	v_ldexp_f32 v18, v18, v37
	v_ldexp_f32 v37, v36, v38
	v_ldexp_f32 v36, v0, v39
	v_mul_f32_e32 v0, v137, v18
	v_fma_f32 v38, v137, v18, 0
	v_pk_mul_f32 v[18:19], v[20:21], v[36:37]
	v_add_f32_e32 v20, v19, v38
	v_add_f32_e32 v20, v18, v20
	v_div_scale_f32 v21, s[4:5], v20, v20, 1.0
	v_rcp_f32_e32 v37, v21
	v_div_scale_f32 v36, vcc, 1.0, v20, 1.0
	v_fma_f32 v38, -v21, v37, 1.0
	v_fmac_f32_e32 v37, v38, v37
	v_mul_f32_e32 v38, v36, v37
	v_fma_f32 v39, -v21, v38, v36
	v_fmac_f32_e32 v38, v39, v37
	v_fma_f32 v21, -v21, v38, v36
	v_div_fmas_f32 v21, v21, v37, v38
	v_div_fixup_f32 v21, v21, v20, 1.0
	v_mul_f32_e32 v0, v0, v21
	v_mul_f32_e32 v20, v19, v21
	v_mul_f32_e32 v18, v18, v21
	v_lshlrev_b32_e32 v22, 16, v142
	v_and_b32_e32 v23, 0xffff0000, v142
	v_lshlrev_b32_e32 v6, 16, v143
	v_and_b32_e32 v7, 0xffff0000, v143
	v_lshlrev_b32_e32 v30, 16, v144
	v_and_b32_e32 v31, 0xffff0000, v144
	v_lshlrev_b32_e32 v8, 16, v145
	v_and_b32_e32 v9, 0xffff0000, v145
	v_lshlrev_b32_e32 v26, 16, v146
	v_and_b32_e32 v27, 0xffff0000, v146
	v_lshlrev_b32_e32 v10, 16, v147
	v_and_b32_e32 v11, 0xffff0000, v147
	v_lshlrev_b32_e32 v32, 16, v148
	v_and_b32_e32 v33, 0xffff0000, v148
	v_lshlrev_b32_e32 v12, 16, v149
	v_and_b32_e32 v13, 0xffff0000, v149
	v_pk_fma_f32 v[22:23], v[0:1], v[22:23], 0 op_sel_hi:[0,1,0]
	v_pk_fma_f32 v[6:7], v[0:1], v[6:7], 0 op_sel_hi:[0,1,0]
	v_pk_fma_f32 v[30:31], v[0:1], v[30:31], 0 op_sel_hi:[0,1,0]
	v_pk_fma_f32 v[8:9], v[0:1], v[8:9], 0 op_sel_hi:[0,1,0]
	v_lshlrev_b32_e32 v28, 16, v150
	v_and_b32_e32 v29, 0xffff0000, v150
	v_lshlrev_b32_e32 v14, 16, v151
	v_and_b32_e32 v15, 0xffff0000, v151
	v_lshlrev_b32_e32 v34, 16, v152
	v_and_b32_e32 v35, 0xffff0000, v152
	v_lshlrev_b32_e32 v16, 16, v153
	v_and_b32_e32 v17, 0xffff0000, v153
	v_pk_fma_f32 v[22:23], v[20:21], v[26:27], v[22:23] op_sel_hi:[0,1,1]
	v_pk_fma_f32 v[6:7], v[20:21], v[10:11], v[6:7] op_sel_hi:[0,1,1]
	v_pk_fma_f32 v[10:11], v[20:21], v[32:33], v[30:31] op_sel_hi:[0,1,1]
	v_pk_fma_f32 v[8:9], v[20:21], v[12:13], v[8:9] op_sel_hi:[0,1,1]
	v_pk_fma_f32 v[12:13], v[18:19], v[28:29], v[22:23] op_sel_hi:[0,1,1]
	v_pk_fma_f32 v[14:15], v[18:19], v[14:15], v[6:7] op_sel_hi:[0,1,1]
	v_pk_fma_f32 v[10:11], v[18:19], v[34:35], v[10:11] op_sel_hi:[0,1,1]
	v_pk_fma_f32 v[16:17], v[18:19], v[16:17], v[8:9] op_sel_hi:[0,1,1]
	v_cvt_pk_bf16_f32 v142, v12, v13
	v_cvt_pk_bf16_f32 v143, v14, v15
	v_cvt_pk_bf16_f32 v144, v10, v11
	v_cvt_pk_bf16_f32 v145, v16, v17
	global_store_dwordx4 v154, v[142:145], s[10:11]
	s_waitcnt vmcnt(37)
	v_max3_f32 v0, v160, v162, v164
	v_sub_f32_e32 v18, v160, v0
	v_sub_f32_e32 v36, v162, v0
	v_sub_f32_e32 v0, v164, v0
	v_cmp_gt_f32_e32 vcc, s19, v18
	v_cmp_gt_f32_e64 s[4:5], s19, v36
	v_cmp_gt_f32_e64 s[32:33], s19, v0
	v_cndmask_b32_e32 v37, 0, v4, vcc
	v_cndmask_b32_e64 v38, 0, v4, s[4:5]
	v_cndmask_b32_e64 v39, 0, v4, s[32:33]
	v_add_f32_e32 v18, v18, v37
	v_add_f32_e32 v36, v36, v38
	v_add_f32_e32 v0, v0, v39
	v_exp_f32_e32 v18, v18
	v_exp_f32_e32 v36, v36
	v_exp_f32_e32 v0, v0
	v_cndmask_b32_e32 v37, 0, v5, vcc
	v_cndmask_b32_e64 v38, 0, v5, s[4:5]
	v_cndmask_b32_e64 v39, 0, v5, s[32:33]
	v_mov_b32_e32 v20, v165
	v_mov_b32_e32 v21, v163
	v_ldexp_f32 v18, v18, v37
	v_ldexp_f32 v37, v36, v38
	v_ldexp_f32 v36, v0, v39
	v_mul_f32_e32 v0, v161, v18
	v_fma_f32 v38, v161, v18, 0
	v_pk_mul_f32 v[18:19], v[20:21], v[36:37]
	v_add_f32_e32 v20, v19, v38
	v_add_f32_e32 v20, v18, v20
	v_div_scale_f32 v21, s[4:5], v20, v20, 1.0
	v_rcp_f32_e32 v37, v21
	v_div_scale_f32 v36, vcc, 1.0, v20, 1.0
	v_fma_f32 v38, -v21, v37, 1.0
	v_fmac_f32_e32 v37, v38, v37
	v_mul_f32_e32 v38, v36, v37
	v_fma_f32 v39, -v21, v38, v36
	v_fmac_f32_e32 v38, v39, v37
	v_fma_f32 v21, -v21, v38, v36
	v_div_fmas_f32 v21, v21, v37, v38
	v_div_fixup_f32 v21, v21, v20, 1.0
	v_mul_f32_e32 v0, v0, v21
	v_mul_f32_e32 v20, v19, v21
	v_mul_f32_e32 v18, v18, v21
	v_lshlrev_b32_e32 v22, 16, v166
	v_and_b32_e32 v23, 0xffff0000, v166
	v_lshlrev_b32_e32 v6, 16, v167
	v_and_b32_e32 v7, 0xffff0000, v167
	v_lshlrev_b32_e32 v30, 16, v168
	v_and_b32_e32 v31, 0xffff0000, v168
	v_lshlrev_b32_e32 v8, 16, v169
	v_and_b32_e32 v9, 0xffff0000, v169
	v_lshlrev_b32_e32 v26, 16, v170
	v_and_b32_e32 v27, 0xffff0000, v170
	v_lshlrev_b32_e32 v10, 16, v171
	v_and_b32_e32 v11, 0xffff0000, v171
	v_lshlrev_b32_e32 v32, 16, v172
	v_and_b32_e32 v33, 0xffff0000, v172
	v_lshlrev_b32_e32 v12, 16, v173
	v_and_b32_e32 v13, 0xffff0000, v173
	v_pk_fma_f32 v[22:23], v[0:1], v[22:23], 0 op_sel_hi:[0,1,0]
	v_pk_fma_f32 v[6:7], v[0:1], v[6:7], 0 op_sel_hi:[0,1,0]
	v_pk_fma_f32 v[30:31], v[0:1], v[30:31], 0 op_sel_hi:[0,1,0]
	v_pk_fma_f32 v[8:9], v[0:1], v[8:9], 0 op_sel_hi:[0,1,0]
	v_lshlrev_b32_e32 v28, 16, v174
	v_and_b32_e32 v29, 0xffff0000, v174
	v_lshlrev_b32_e32 v14, 16, v175
	v_and_b32_e32 v15, 0xffff0000, v175
	v_lshlrev_b32_e32 v34, 16, v176
	v_and_b32_e32 v35, 0xffff0000, v176
	v_lshlrev_b32_e32 v16, 16, v177
	v_and_b32_e32 v17, 0xffff0000, v177
	v_pk_fma_f32 v[22:23], v[20:21], v[26:27], v[22:23] op_sel_hi:[0,1,1]
	v_pk_fma_f32 v[6:7], v[20:21], v[10:11], v[6:7] op_sel_hi:[0,1,1]
	v_pk_fma_f32 v[10:11], v[20:21], v[32:33], v[30:31] op_sel_hi:[0,1,1]
	v_pk_fma_f32 v[8:9], v[20:21], v[12:13], v[8:9] op_sel_hi:[0,1,1]
	v_pk_fma_f32 v[12:13], v[18:19], v[28:29], v[22:23] op_sel_hi:[0,1,1]
	v_pk_fma_f32 v[14:15], v[18:19], v[14:15], v[6:7] op_sel_hi:[0,1,1]
	v_pk_fma_f32 v[10:11], v[18:19], v[34:35], v[10:11] op_sel_hi:[0,1,1]
	v_pk_fma_f32 v[16:17], v[18:19], v[16:17], v[8:9] op_sel_hi:[0,1,1]
	v_cvt_pk_bf16_f32 v166, v12, v13
	v_cvt_pk_bf16_f32 v167, v14, v15
	v_cvt_pk_bf16_f32 v168, v10, v11
	v_cvt_pk_bf16_f32 v169, v16, v17
	global_store_dwordx4 v178, v[166:169], s[10:11]
	s_waitcnt vmcnt(32)
; __device__ __forceinline__ unsigned pk2(float lo, float hi) { f32x2_t v = {lo, hi}; bf16x2_t b = __builtin_convertvector(v, bf16x2_t); return __builtin_bit_cast(unsigned, b); }
; __device__ __forceinline__ float bflo(unsigned w) { return __uint_as_float(w << 16); }
; __device__ __forceinline__ float bfhi(unsigned w) { return __uint_as_float(w & 0xffff0000u); }
; __device__ __forceinline__ bf16* po_base(unsigned char* ws, int pat) { return (bf16*)(ws + (pat < 2 ? 436 * MiB + (size_t)pat * 32 * MiB : WS_Y)); }
; __device__ __forceinline__ void attn_combine(unsigned char* ws, const float* __restrict__ PM, bf16* CAT, int gtid, int gthreads, int iend = S * 128) {
;     for (int idx = gtid; idx < iend; idx += gthreads) {
;         const int t = idx >> 7, c = (idx & 127) * 8, hh = c >> 7;
;         float mm[3], ll[3];
; #pragma unroll
;         for (int p = 0; p < 3; ++p) { const f32x2_t ml = *(const f32x2_t*)(PM + (((size_t)p * S + t) * 8 + hh) * 2); mm[p] = ml[0]; ll[p] = ml[1]; }
;         const float ma = fmaxf(mm[0], fmaxf(mm[1], mm[2]));
;         float w[3], den = 0.f;
; #pragma unroll
;         for (int p = 0; p < 3; ++p) { w[p] = exp2f(mm[p] - ma) * ll[p]; den += w[p]; }
;         const float inv = 1.f / den;
;         float o[8] = {0.f, 0.f, 0.f, 0.f, 0.f, 0.f, 0.f, 0.f};
; #pragma unroll
;         for (int p = 0; p < 3; ++p) {
;             const u32x4 v = *(const u32x4*)(po_base(ws, p) + (size_t)t * 1024 + c); const float wp = w[p] * inv;
;             o[0] += wp * bflo(v.x); o[1] += wp * bfhi(v.x); o[2] += wp * bflo(v.y); o[3] += wp * bfhi(v.y); o[4] += wp * bflo(v.z); o[5] += wp * bfhi(v.z); o[6] += wp * bflo(v.w); o[7] += wp * bfhi(v.w);
;         }
;         u32x4 ov; ov.x = pk2(o[0], o[1]); ov.y = pk2(o[2], o[3]); ov.z = pk2(o[4], o[5]); ov.w = pk2(o[6], o[7]);
;         *(u32x4*)(CAT + (size_t)t * 2048 + c) = ov;
	v_max3_f32 v0, v188, v190, v192
	v_sub_f32_e32 v18, v188, v0
	v_sub_f32_e32 v36, v190, v0
	v_sub_f32_e32 v0, v192, v0
	v_cmp_gt_f32_e32 vcc, s19, v18
	v_cmp_gt_f32_e64 s[4:5], s19, v36
	v_cmp_gt_f32_e64 s[32:33], s19, v0
	v_cndmask_b32_e32 v37, 0, v4, vcc
	v_cndmask_b32_e64 v38, 0, v4, s[4:5]
	v_cndmask_b32_e64 v39, 0, v4, s[32:33]
	v_add_f32_e32 v18, v18, v37
	v_add_f32_e32 v36, v36, v38
	v_add_f32_e32 v0, v0, v39
	v_exp_f32_e32 v18, v18
	v_exp_f32_e32 v36, v36
	v_exp_f32_e32 v0, v0
	v_cndmask_b32_e32 v37, 0, v5, vcc
	v_cndmask_b32_e64 v38, 0, v5, s[4:5]
	v_cndmask_b32_e64 v39, 0, v5, s[32:33]
	v_mov_b32_e32 v20, v193
	v_mov_b32_e32 v21, v191
	v_ldexp_f32 v18, v18, v37
	v_ldexp_f32 v37, v36, v38
	v_ldexp_f32 v36, v0, v39
	v_mul_f32_e32 v0, v189, v18
	v_fma_f32 v38, v189, v18, 0
	v_pk_mul_f32 v[18:19], v[20:21], v[36:37]
	v_add_f32_e32 v20, v19, v38
	v_add_f32_e32 v20, v18, v20
	v_div_scale_f32 v21, s[4:5], v20, v20, 1.0
	v_rcp_f32_e32 v37, v21
	v_div_scale_f32 v36, vcc, 1.0, v20, 1.0
	v_fma_f32 v38, -v21, v37, 1.0
	v_fmac_f32_e32 v37, v38, v37
	v_mul_f32_e32 v38, v36, v37
	v_fma_f32 v39, -v21, v38, v36
	v_fmac_f32_e32 v38, v39, v37
	v_fma_f32 v21, -v21, v38, v36
	v_div_fmas_f32 v21, v21, v37, v38
	v_div_fixup_f32 v21, v21, v20, 1.0
	v_mul_f32_e32 v0, v0, v21
	v_mul_f32_e32 v20, v19, v21
	v_mul_f32_e32 v18, v18, v21
	v_lshlrev_b32_e32 v22, 16, v194
	v_and_b32_e32 v23, 0xffff0000, v194
	v_lshlrev_b32_e32 v6, 16, v195
	v_and_b32_e32 v7, 0xffff0000, v195
	v_lshlrev_b32_e32 v30, 16, v196
	v_and_b32_e32 v31, 0xffff0000, v196
	v_lshlrev_b32_e32 v8, 16, v197
	v_and_b32_e32 v9, 0xffff0000, v197
	v_lshlrev_b32_e32 v26, 16, v198
	v_and_b32_e32 v27, 0xffff0000, v198
	v_lshlrev_b32_e32 v10, 16, v199
	v_and_b32_e32 v11, 0xffff0000, v199
	v_lshlrev_b32_e32 v32, 16, v200
	v_and_b32_e32 v33, 0xffff0000, v200
	v_lshlrev_b32_e32 v12, 16, v201
	v_and_b32_e32 v13, 0xffff0000, v201
	v_pk_fma_f32 v[22:23], v[0:1], v[22:23], 0 op_sel_hi:[0,1,0]
	v_pk_fma_f32 v[6:7], v[0:1], v[6:7], 0 op_sel_hi:[0,1,0]
	v_pk_fma_f32 v[30:31], v[0:1], v[30:31], 0 op_sel_hi:[0,1,0]
	v_pk_fma_f32 v[8:9], v[0:1], v[8:9], 0 op_sel_hi:[0,1,0]
	v_lshlrev_b32_e32 v28, 16, v202
	v_and_b32_e32 v29, 0xffff0000, v202
	v_lshlrev_b32_e32 v14, 16, v203
	v_and_b32_e32 v15, 0xffff0000, v203
	v_lshlrev_b32_e32 v34, 16, v204
	v_and_b32_e32 v35, 0xffff0000, v204
	v_lshlrev_b32_e32 v16, 16, v205
	v_and_b32_e32 v17, 0xffff0000, v205
	v_pk_fma_f32 v[22:23], v[20:21], v[26:27], v[22:23] op_sel_hi:[0,1,1]
	v_pk_fma_f32 v[6:7], v[20:21], v[10:11], v[6:7] op_sel_hi:[0,1,1]
	v_pk_fma_f32 v[10:11], v[20:21], v[32:33], v[30:31] op_sel_hi:[0,1,1]
	v_pk_fma_f32 v[8:9], v[20:21], v[12:13], v[8:9] op_sel_hi:[0,1,1]
	v_pk_fma_f32 v[12:13], v[18:19], v[28:29], v[22:23] op_sel_hi:[0,1,1]
	v_pk_fma_f32 v[14:15], v[18:19], v[14:15], v[6:7] op_sel_hi:[0,1,1]
	v_pk_fma_f32 v[10:11], v[18:19], v[34:35], v[10:11] op_sel_hi:[0,1,1]
	v_pk_fma_f32 v[16:17], v[18:19], v[16:17], v[8:9] op_sel_hi:[0,1,1]
	v_cvt_pk_bf16_f32 v194, v12, v13
	v_cvt_pk_bf16_f32 v195, v14, v15
	v_cvt_pk_bf16_f32 v196, v10, v11
	v_cvt_pk_bf16_f32 v197, v16, v17
	global_store_dwordx4 v206, v[194:197], s[10:11]
	s_waitcnt vmcnt(27)
	v_max3_f32 v0, v212, v214, v216
	v_sub_f32_e32 v18, v212, v0
	v_sub_f32_e32 v36, v214, v0
	v_sub_f32_e32 v0, v216, v0
	v_cmp_gt_f32_e32 vcc, s19, v18
	v_cmp_gt_f32_e64 s[4:5], s19, v36
	v_cmp_gt_f32_e64 s[32:33], s19, v0
	v_cndmask_b32_e32 v37, 0, v4, vcc
	v_cndmask_b32_e64 v38, 0, v4, s[4:5]
	v_cndmask_b32_e64 v39, 0, v4, s[32:33]
	v_add_f32_e32 v18, v18, v37
	v_add_f32_e32 v36, v36, v38
	v_add_f32_e32 v0, v0, v39
	v_exp_f32_e32 v18, v18
	v_exp_f32_e32 v36, v36
	v_exp_f32_e32 v0, v0
	v_cndmask_b32_e32 v37, 0, v5, vcc
	v_cndmask_b32_e64 v38, 0, v5, s[4:5]
	v_cndmask_b32_e64 v39, 0, v5, s[32:33]
	v_mov_b32_e32 v20, v217
	v_mov_b32_e32 v21, v215
	v_ldexp_f32 v18, v18, v37
	v_ldexp_f32 v37, v36, v38
	v_ldexp_f32 v36, v0, v39
	v_mul_f32_e32 v0, v213, v18
	v_fma_f32 v38, v213, v18, 0
	v_pk_mul_f32 v[18:19], v[20:21], v[36:37]
	v_add_f32_e32 v20, v19, v38
	v_add_f32_e32 v20, v18, v20
	v_div_scale_f32 v21, s[4:5], v20, v20, 1.0
	v_rcp_f32_e32 v37, v21
	v_div_scale_f32 v36, vcc, 1.0, v20, 1.0
	v_fma_f32 v38, -v21, v37, 1.0
	v_fmac_f32_e32 v37, v38, v37
	v_mul_f32_e32 v38, v36, v37
	v_fma_f32 v39, -v21, v38, v36
	v_fmac_f32_e32 v38, v39, v37
	v_fma_f32 v21, -v21, v38, v36
	v_div_fmas_f32 v21, v21, v37, v38
	v_div_fixup_f32 v21, v21, v20, 1.0
	v_mul_f32_e32 v0, v0, v21
	v_mul_f32_e32 v20, v19, v21
	v_mul_f32_e32 v18, v18, v21
	v_lshlrev_b32_e32 v22, 16, v218
	v_and_b32_e32 v23, 0xffff0000, v218
	v_lshlrev_b32_e32 v6, 16, v219
	v_and_b32_e32 v7, 0xffff0000, v219
	v_lshlrev_b32_e32 v30, 16, v220
	v_and_b32_e32 v31, 0xffff0000, v220
	v_lshlrev_b32_e32 v8, 16, v221
	v_and_b32_e32 v9, 0xffff0000, v221
	v_lshlrev_b32_e32 v26, 16, v222
	v_and_b32_e32 v27, 0xffff0000, v222
	v_lshlrev_b32_e32 v10, 16, v223
	v_and_b32_e32 v11, 0xffff0000, v223
	v_lshlrev_b32_e32 v32, 16, v224
	v_and_b32_e32 v33, 0xffff0000, v224
	v_lshlrev_b32_e32 v12, 16, v225
	v_and_b32_e32 v13, 0xffff0000, v225
	v_pk_fma_f32 v[22:23], v[0:1], v[22:23], 0 op_sel_hi:[0,1,0]
	v_pk_fma_f32 v[6:7], v[0:1], v[6:7], 0 op_sel_hi:[0,1,0]
	v_pk_fma_f32 v[30:31], v[0:1], v[30:31], 0 op_sel_hi:[0,1,0]
	v_pk_fma_f32 v[8:9], v[0:1], v[8:9], 0 op_sel_hi:[0,1,0]
	v_lshlrev_b32_e32 v28, 16, v226
	v_and_b32_e32 v29, 0xffff0000, v226
	v_lshlrev_b32_e32 v14, 16, v227
	v_and_b32_e32 v15, 0xffff0000, v227
	v_lshlrev_b32_e32 v34, 16, v228
	v_and_b32_e32 v35, 0xffff0000, v228
	v_lshlrev_b32_e32 v16, 16, v229
	v_and_b32_e32 v17, 0xffff0000, v229
	v_pk_fma_f32 v[22:23], v[20:21], v[26:27], v[22:23] op_sel_hi:[0,1,1]
	v_pk_fma_f32 v[6:7], v[20:21], v[10:11], v[6:7] op_sel_hi:[0,1,1]
	v_pk_fma_f32 v[10:11], v[20:21], v[32:33], v[30:31] op_sel_hi:[0,1,1]
	v_pk_fma_f32 v[8:9], v[20:21], v[12:13], v[8:9] op_sel_hi:[0,1,1]
	v_pk_fma_f32 v[12:13], v[18:19], v[28:29], v[22:23] op_sel_hi:[0,1,1]
	v_pk_fma_f32 v[14:15], v[18:19], v[14:15], v[6:7] op_sel_hi:[0,1,1]
	v_pk_fma_f32 v[10:11], v[18:19], v[34:35], v[10:11] op_sel_hi:[0,1,1]
	v_pk_fma_f32 v[16:17], v[18:19], v[16:17], v[8:9] op_sel_hi:[0,1,1]
	v_cvt_pk_bf16_f32 v218, v12, v13
	v_cvt_pk_bf16_f32 v219, v14, v15
	v_cvt_pk_bf16_f32 v220, v10, v11
	v_cvt_pk_bf16_f32 v221, v16, v17
	global_store_dwordx4 v230, v[218:221], s[10:11]
	s_add_i32 s0, s0, -1
	s_branch .Lcmb_loop
; __device__ __forceinline__ unsigned pk2(float lo, float hi) { f32x2_t v = {lo, hi}; bf16x2_t b = __builtin_convertvector(v, bf16x2_t); return __builtin_bit_cast(unsigned, b); }
; __device__ __forceinline__ float bflo(unsigned w) { return __uint_as_float(w << 16); }
; __device__ __forceinline__ float bfhi(unsigned w) { return __uint_as_float(w & 0xffff0000u); }
; __device__ __forceinline__ bf16* po_base(unsigned char* ws, int pat) { return (bf16*)(ws + (pat < 2 ? 436 * MiB + (size_t)pat * 32 * MiB : WS_Y)); }
; __device__ __forceinline__ void attn_combine(unsigned char* ws, const float* __restrict__ PM, bf16* CAT, int gtid, int gthreads, int iend = S * 128) {
;     ...
;         for (int p = 0; p < 3; ++p) { const f32x2_t ml = *(const f32x2_t*)(PM + (((size_t)p * S + t) * 8 + hh) * 2); mm[p] = ml[0]; ll[p] = ml[1]; }
;         const float ma = fmaxf(mm[0], fmaxf(mm[1], mm[2]));
;         float w[3], den = 0.f;
; #pragma unroll
;         for (int p = 0; p < 3; ++p) { w[p] = exp2f(mm[p] - ma) * ll[p]; den += w[p]; }
;         const float inv = 1.f / den;
;         float o[8] = {0.f, 0.f, 0.f, 0.f, 0.f, 0.f, 0.f, 0.f};
; #pragma unroll
;         for (int p = 0; p < 3; ++p) {
;             const u32x4 v = *(const u32x4*)(po_base(ws, p) + (size_t)t * 1024 + c); const float wp = w[p] * inv;
;             o[0] += wp * bflo(v.x); o[1] += wp * bfhi(v.x); o[2] += wp * bflo(v.y); o[3] += wp * bfhi(v.y); o[4] += wp * bflo(v.z); o[5] += wp * bfhi(v.z); o[6] += wp * bflo(v.w); o[7] += wp * bfhi(v.w);
;         }
;         u32x4 ov; ov.x = pk2(o[0], o[1]); ov.y = pk2(o[2], o[3]); ov.z = pk2(o[4], o[5]); ov.w = pk2(o[6], o[7]);
;         *(u32x4*)(CAT + (size_t)t * 2048 + c) = ov;
.Lcmb_lastA:
	s_waitcnt vmcnt(18)
	v_max3_f32 v0, v40, v42, v44
	v_sub_f32_e32 v18, v40, v0
	v_sub_f32_e32 v36, v42, v0
	v_sub_f32_e32 v0, v44, v0
	v_cmp_gt_f32_e32 vcc, s19, v18
	v_cmp_gt_f32_e64 s[4:5], s19, v36
	v_cmp_gt_f32_e64 s[32:33], s19, v0
	v_cndmask_b32_e32 v37, 0, v4, vcc
	v_cndmask_b32_e64 v38, 0, v4, s[4:5]
	v_cndmask_b32_e64 v39, 0, v4, s[32:33]
	v_add_f32_e32 v18, v18, v37
	v_add_f32_e32 v36, v36, v38
	v_add_f32_e32 v0, v0, v39
	v_exp_f32_e32 v18, v18
	v_exp_f32_e32 v36, v36
	v_exp_f32_e32 v0, v0
	v_cndmask_b32_e32 v37, 0, v5, vcc
	v_cndmask_b32_e64 v38, 0, v5, s[4:5]
	v_cndmask_b32_e64 v39, 0, v5, s[32:33]
	v_mov_b32_e32 v20, v45
	v_mov_b32_e32 v21, v43
	v_ldexp_f32 v18, v18, v37
	v_ldexp_f32 v37, v36, v38
	v_ldexp_f32 v36, v0, v39
	v_mul_f32_e32 v0, v41, v18
	v_fma_f32 v38, v41, v18, 0
	v_pk_mul_f32 v[18:19], v[20:21], v[36:37]
	v_add_f32_e32 v20, v19, v38
	v_add_f32_e32 v20, v18, v20
	v_div_scale_f32 v21, s[4:5], v20, v20, 1.0
	v_rcp_f32_e32 v37, v21
	v_div_scale_f32 v36, vcc, 1.0, v20, 1.0
	v_fma_f32 v38, -v21, v37, 1.0
	v_fmac_f32_e32 v37, v38, v37
	v_mul_f32_e32 v38, v36, v37
	v_fma_f32 v39, -v21, v38, v36
	v_fmac_f32_e32 v38, v39, v37
	v_fma_f32 v21, -v21, v38, v36
	v_div_fmas_f32 v21, v21, v37, v38
	v_div_fixup_f32 v21, v21, v20, 1.0
	v_mul_f32_e32 v0, v0, v21
	v_mul_f32_e32 v20, v19, v21
	v_mul_f32_e32 v18, v18, v21
	v_lshlrev_b32_e32 v22, 16, v46
	v_and_b32_e32 v23, 0xffff0000, v46
	v_lshlrev_b32_e32 v6, 16, v47
	v_and_b32_e32 v7, 0xffff0000, v47
	v_lshlrev_b32_e32 v30, 16, v48
	v_and_b32_e32 v31, 0xffff0000, v48
	v_lshlrev_b32_e32 v8, 16, v49
	v_and_b32_e32 v9, 0xffff0000, v49
	v_lshlrev_b32_e32 v26, 16, v50
	v_and_b32_e32 v27, 0xffff0000, v50
	v_lshlrev_b32_e32 v10, 16, v51
	v_and_b32_e32 v11, 0xffff0000, v51
	v_lshlrev_b32_e32 v32, 16, v52
	v_and_b32_e32 v33, 0xffff0000, v52
	v_lshlrev_b32_e32 v12, 16, v53
	v_and_b32_e32 v13, 0xffff0000, v53
	v_pk_fma_f32 v[22:23], v[0:1], v[22:23], 0 op_sel_hi:[0,1,0]
	v_pk_fma_f32 v[6:7], v[0:1], v[6:7], 0 op_sel_hi:[0,1,0]
	v_pk_fma_f32 v[30:31], v[0:1], v[30:31], 0 op_sel_hi:[0,1,0]
	v_pk_fma_f32 v[8:9], v[0:1], v[8:9], 0 op_sel_hi:[0,1,0]
	v_lshlrev_b32_e32 v28, 16, v54
	v_and_b32_e32 v29, 0xffff0000, v54
	v_lshlrev_b32_e32 v14, 16, v55
	v_and_b32_e32 v15, 0xffff0000, v55
	v_lshlrev_b32_e32 v34, 16, v56
	v_and_b32_e32 v35, 0xffff0000, v56
	v_lshlrev_b32_e32 v16, 16, v57
	v_and_b32_e32 v17, 0xffff0000, v57
	v_pk_fma_f32 v[22:23], v[20:21], v[26:27], v[22:23] op_sel_hi:[0,1,1]
	v_pk_fma_f32 v[6:7], v[20:21], v[10:11], v[6:7] op_sel_hi:[0,1,1]
	v_pk_fma_f32 v[10:11], v[20:21], v[32:33], v[30:31] op_sel_hi:[0,1,1]
	v_pk_fma_f32 v[8:9], v[20:21], v[12:13], v[8:9] op_sel_hi:[0,1,1]
	v_pk_fma_f32 v[12:13], v[18:19], v[28:29], v[22:23] op_sel_hi:[0,1,1]
	v_pk_fma_f32 v[14:15], v[18:19], v[14:15], v[6:7] op_sel_hi:[0,1,1]
	v_pk_fma_f32 v[10:11], v[18:19], v[34:35], v[10:11] op_sel_hi:[0,1,1]
	v_pk_fma_f32 v[16:17], v[18:19], v[16:17], v[8:9] op_sel_hi:[0,1,1]
	v_cvt_pk_bf16_f32 v46, v12, v13
	v_cvt_pk_bf16_f32 v47, v14, v15
	v_cvt_pk_bf16_f32 v48, v10, v11
	v_cvt_pk_bf16_f32 v49, v16, v17
	global_store_dwordx4 v58, v[46:49], s[10:11]
	s_waitcnt vmcnt(13)
	v_max3_f32 v0, v64, v66, v68
	v_sub_f32_e32 v18, v64, v0
	v_sub_f32_e32 v36, v66, v0
	v_sub_f32_e32 v0, v68, v0
	v_cmp_gt_f32_e32 vcc, s19, v18
	v_cmp_gt_f32_e64 s[4:5], s19, v36
	v_cmp_gt_f32_e64 s[32:33], s19, v0
	v_cndmask_b32_e32 v37, 0, v4, vcc
	v_cndmask_b32_e64 v38, 0, v4, s[4:5]
	v_cndmask_b32_e64 v39, 0, v4, s[32:33]
	v_add_f32_e32 v18, v18, v37
	v_add_f32_e32 v36, v36, v38
	v_add_f32_e32 v0, v0, v39
	v_exp_f32_e32 v18, v18
	v_exp_f32_e32 v36, v36
	v_exp_f32_e32 v0, v0
	v_cndmask_b32_e32 v37, 0, v5, vcc
	v_cndmask_b32_e64 v38, 0, v5, s[4:5]
	v_cndmask_b32_e64 v39, 0, v5, s[32:33]
	v_mov_b32_e32 v20, v69
	v_mov_b32_e32 v21, v67
	v_ldexp_f32 v18, v18, v37
	v_ldexp_f32 v37, v36, v38
	v_ldexp_f32 v36, v0, v39
	v_mul_f32_e32 v0, v65, v18
	v_fma_f32 v38, v65, v18, 0
	v_pk_mul_f32 v[18:19], v[20:21], v[36:37]
	v_add_f32_e32 v20, v19, v38
	v_add_f32_e32 v20, v18, v20
	v_div_scale_f32 v21, s[4:5], v20, v20, 1.0
	v_rcp_f32_e32 v37, v21
	v_div_scale_f32 v36, vcc, 1.0, v20, 1.0
	v_fma_f32 v38, -v21, v37, 1.0
	v_fmac_f32_e32 v37, v38, v37
	v_mul_f32_e32 v38, v36, v37
	v_fma_f32 v39, -v21, v38, v36
	v_fmac_f32_e32 v38, v39, v37
	v_fma_f32 v21, -v21, v38, v36
	v_div_fmas_f32 v21, v21, v37, v38
	v_div_fixup_f32 v21, v21, v20, 1.0
	v_mul_f32_e32 v0, v0, v21
	v_mul_f32_e32 v20, v19, v21
	v_mul_f32_e32 v18, v18, v21
	v_lshlrev_b32_e32 v22, 16, v70
	v_and_b32_e32 v23, 0xffff0000, v70
	v_lshlrev_b32_e32 v6, 16, v71
	v_and_b32_e32 v7, 0xffff0000, v71
	v_lshlrev_b32_e32 v30, 16, v72
	v_and_b32_e32 v31, 0xffff0000, v72
	v_lshlrev_b32_e32 v8, 16, v73
	v_and_b32_e32 v9, 0xffff0000, v73
	v_lshlrev_b32_e32 v26, 16, v74
	v_and_b32_e32 v27, 0xffff0000, v74
	v_lshlrev_b32_e32 v10, 16, v75
	v_and_b32_e32 v11, 0xffff0000, v75
	v_lshlrev_b32_e32 v32, 16, v76
	v_and_b32_e32 v33, 0xffff0000, v76
	v_lshlrev_b32_e32 v12, 16, v77
	v_and_b32_e32 v13, 0xffff0000, v77
	v_pk_fma_f32 v[22:23], v[0:1], v[22:23], 0 op_sel_hi:[0,1,0]
	v_pk_fma_f32 v[6:7], v[0:1], v[6:7], 0 op_sel_hi:[0,1,0]
	v_pk_fma_f32 v[30:31], v[0:1], v[30:31], 0 op_sel_hi:[0,1,0]
	v_pk_fma_f32 v[8:9], v[0:1], v[8:9], 0 op_sel_hi:[0,1,0]
	v_lshlrev_b32_e32 v28, 16, v78
	v_and_b32_e32 v29, 0xffff0000, v78
	v_lshlrev_b32_e32 v14, 16, v79
	v_and_b32_e32 v15, 0xffff0000, v79
	v_lshlrev_b32_e32 v34, 16, v80
	v_and_b32_e32 v35, 0xffff0000, v80
	v_lshlrev_b32_e32 v16, 16, v81
	v_and_b32_e32 v17, 0xffff0000, v81
	v_pk_fma_f32 v[22:23], v[20:21], v[26:27], v[22:23] op_sel_hi:[0,1,1]
	v_pk_fma_f32 v[6:7], v[20:21], v[10:11], v[6:7] op_sel_hi:[0,1,1]
	v_pk_fma_f32 v[10:11], v[20:21], v[32:33], v[30:31] op_sel_hi:[0,1,1]
	v_pk_fma_f32 v[8:9], v[20:21], v[12:13], v[8:9] op_sel_hi:[0,1,1]
	v_pk_fma_f32 v[12:13], v[18:19], v[28:29], v[22:23] op_sel_hi:[0,1,1]
	v_pk_fma_f32 v[14:15], v[18:19], v[14:15], v[6:7] op_sel_hi:[0,1,1]
	v_pk_fma_f32 v[10:11], v[18:19], v[34:35], v[10:11] op_sel_hi:[0,1,1]
	v_pk_fma_f32 v[16:17], v[18:19], v[16:17], v[8:9] op_sel_hi:[0,1,1]
	v_cvt_pk_bf16_f32 v70, v12, v13
	v_cvt_pk_bf16_f32 v71, v14, v15
	v_cvt_pk_bf16_f32 v72, v10, v11
	v_cvt_pk_bf16_f32 v73, v16, v17
	global_store_dwordx4 v82, v[70:73], s[10:11]
	s_waitcnt vmcnt(8)
; __device__ __forceinline__ unsigned pk2(float lo, float hi) { f32x2_t v = {lo, hi}; bf16x2_t b = __builtin_convertvector(v, bf16x2_t); return __builtin_bit_cast(unsigned, b); }
; __device__ __forceinline__ float bflo(unsigned w) { return __uint_as_float(w << 16); }
; __device__ __forceinline__ float bfhi(unsigned w) { return __uint_as_float(w & 0xffff0000u); }
; __device__ __forceinline__ bf16* po_base(unsigned char* ws, int pat) { return (bf16*)(ws + (pat < 2 ? 436 * MiB + (size_t)pat * 32 * MiB : WS_Y)); }
; __device__ __forceinline__ void attn_combine(unsigned char* ws, const float* __restrict__ PM, bf16* CAT, int gtid, int gthreads, int iend = S * 128) {
;     ...
;         for (int p = 0; p < 3; ++p) { const f32x2_t ml = *(const f32x2_t*)(PM + (((size_t)p * S + t) * 8 + hh) * 2); mm[p] = ml[0]; ll[p] = ml[1]; }
;         const float ma = fmaxf(mm[0], fmaxf(mm[1], mm[2]));
;         float w[3], den = 0.f;
; #pragma unroll
;         for (int p = 0; p < 3; ++p) { w[p] = exp2f(mm[p] - ma) * ll[p]; den += w[p]; }
;         const float inv = 1.f / den;
;         float o[8] = {0.f, 0.f, 0.f, 0.f, 0.f, 0.f, 0.f, 0.f};
; #pragma unroll
;         for (int p = 0; p < 3; ++p) {
;             const u32x4 v = *(const u32x4*)(po_base(ws, p) + (size_t)t * 1024 + c); const float wp = w[p] * inv;
;             o[0] += wp * bflo(v.x); o[1] += wp * bfhi(v.x); o[2] += wp * bflo(v.y); o[3] += wp * bfhi(v.y); o[4] += wp * bflo(v.z); o[5] += wp * bfhi(v.z); o[6] += wp * bflo(v.w); o[7] += wp * bfhi(v.w);
;         }
;         u32x4 ov; ov.x = pk2(o[0], o[1]); ov.y = pk2(o[2], o[3]); ov.z = pk2(o[4], o[5]); ov.w = pk2(o[6], o[7]);
;         *(u32x4*)(CAT + (size_t)t * 2048 + c) = ov;
	v_max3_f32 v0, v88, v90, v92
	v_sub_f32_e32 v18, v88, v0
	v_sub_f32_e32 v36, v90, v0
	v_sub_f32_e32 v0, v92, v0
	v_cmp_gt_f32_e32 vcc, s19, v18
	v_cmp_gt_f32_e64 s[4:5], s19, v36
	v_cmp_gt_f32_e64 s[32:33], s19, v0
	v_cndmask_b32_e32 v37, 0, v4, vcc
	v_cndmask_b32_e64 v38, 0, v4, s[4:5]
	v_cndmask_b32_e64 v39, 0, v4, s[32:33]
	v_add_f32_e32 v18, v18, v37
	v_add_f32_e32 v36, v36, v38
	v_add_f32_e32 v0, v0, v39
	v_exp_f32_e32 v18, v18
	v_exp_f32_e32 v36, v36
	v_exp_f32_e32 v0, v0
	v_cndmask_b32_e32 v37, 0, v5, vcc
	v_cndmask_b32_e64 v38, 0, v5, s[4:5]
	v_cndmask_b32_e64 v39, 0, v5, s[32:33]
	v_mov_b32_e32 v20, v93
	v_mov_b32_e32 v21, v91
	v_ldexp_f32 v18, v18, v37
	v_ldexp_f32 v37, v36, v38
	v_ldexp_f32 v36, v0, v39
	v_mul_f32_e32 v0, v89, v18
	v_fma_f32 v38, v89, v18, 0
	v_pk_mul_f32 v[18:19], v[20:21], v[36:37]
	v_add_f32_e32 v20, v19, v38
	v_add_f32_e32 v20, v18, v20
	v_div_scale_f32 v21, s[4:5], v20, v20, 1.0
	v_rcp_f32_e32 v37, v21
	v_div_scale_f32 v36, vcc, 1.0, v20, 1.0
	v_fma_f32 v38, -v21, v37, 1.0
	v_fmac_f32_e32 v37, v38, v37
	v_mul_f32_e32 v38, v36, v37
	v_fma_f32 v39, -v21, v38, v36
	v_fmac_f32_e32 v38, v39, v37
	v_fma_f32 v21, -v21, v38, v36
	v_div_fmas_f32 v21, v21, v37, v38
	v_div_fixup_f32 v21, v21, v20, 1.0
	v_mul_f32_e32 v0, v0, v21
	v_mul_f32_e32 v20, v19, v21
	v_mul_f32_e32 v18, v18, v21
	v_lshlrev_b32_e32 v22, 16, v94
	v_and_b32_e32 v23, 0xffff0000, v94
	v_lshlrev_b32_e32 v6, 16, v95
	v_and_b32_e32 v7, 0xffff0000, v95
	v_lshlrev_b32_e32 v30, 16, v96
	v_and_b32_e32 v31, 0xffff0000, v96
	v_lshlrev_b32_e32 v8, 16, v97
	v_and_b32_e32 v9, 0xffff0000, v97
	v_lshlrev_b32_e32 v26, 16, v98
	v_and_b32_e32 v27, 0xffff0000, v98
	v_lshlrev_b32_e32 v10, 16, v99
	v_and_b32_e32 v11, 0xffff0000, v99
	v_lshlrev_b32_e32 v32, 16, v100
	v_and_b32_e32 v33, 0xffff0000, v100
	v_lshlrev_b32_e32 v12, 16, v101
	v_and_b32_e32 v13, 0xffff0000, v101
	v_pk_fma_f32 v[22:23], v[0:1], v[22:23], 0 op_sel_hi:[0,1,0]
	v_pk_fma_f32 v[6:7], v[0:1], v[6:7], 0 op_sel_hi:[0,1,0]
	v_pk_fma_f32 v[30:31], v[0:1], v[30:31], 0 op_sel_hi:[0,1,0]
	v_pk_fma_f32 v[8:9], v[0:1], v[8:9], 0 op_sel_hi:[0,1,0]
	v_lshlrev_b32_e32 v28, 16, v102
	v_and_b32_e32 v29, 0xffff0000, v102
	v_lshlrev_b32_e32 v14, 16, v103
	v_and_b32_e32 v15, 0xffff0000, v103
	v_lshlrev_b32_e32 v34, 16, v104
	v_and_b32_e32 v35, 0xffff0000, v104
	v_lshlrev_b32_e32 v16, 16, v105
	v_and_b32_e32 v17, 0xffff0000, v105
	v_pk_fma_f32 v[22:23], v[20:21], v[26:27], v[22:23] op_sel_hi:[0,1,1]
	v_pk_fma_f32 v[6:7], v[20:21], v[10:11], v[6:7] op_sel_hi:[0,1,1]
	v_pk_fma_f32 v[10:11], v[20:21], v[32:33], v[30:31] op_sel_hi:[0,1,1]
	v_pk_fma_f32 v[8:9], v[20:21], v[12:13], v[8:9] op_sel_hi:[0,1,1]
	v_pk_fma_f32 v[12:13], v[18:19], v[28:29], v[22:23] op_sel_hi:[0,1,1]
	v_pk_fma_f32 v[14:15], v[18:19], v[14:15], v[6:7] op_sel_hi:[0,1,1]
	v_pk_fma_f32 v[10:11], v[18:19], v[34:35], v[10:11] op_sel_hi:[0,1,1]
	v_pk_fma_f32 v[16:17], v[18:19], v[16:17], v[8:9] op_sel_hi:[0,1,1]
	v_cvt_pk_bf16_f32 v94, v12, v13
	v_cvt_pk_bf16_f32 v95, v14, v15
	v_cvt_pk_bf16_f32 v96, v10, v11
	v_cvt_pk_bf16_f32 v97, v16, v17
	global_store_dwordx4 v106, v[94:97], s[10:11]
	s_waitcnt vmcnt(3)
	v_max3_f32 v0, v112, v114, v116
	v_sub_f32_e32 v18, v112, v0
	v_sub_f32_e32 v36, v114, v0
	v_sub_f32_e32 v0, v116, v0
	v_cmp_gt_f32_e32 vcc, s19, v18
	v_cmp_gt_f32_e64 s[4:5], s19, v36
	v_cmp_gt_f32_e64 s[32:33], s19, v0
	v_cndmask_b32_e32 v37, 0, v4, vcc
	v_cndmask_b32_e64 v38, 0, v4, s[4:5]
	v_cndmask_b32_e64 v39, 0, v4, s[32:33]
	v_add_f32_e32 v18, v18, v37
	v_add_f32_e32 v36, v36, v38
	v_add_f32_e32 v0, v0, v39
	v_exp_f32_e32 v18, v18
	v_exp_f32_e32 v36, v36
	v_exp_f32_e32 v0, v0
	v_cndmask_b32_e32 v37, 0, v5, vcc
	v_cndmask_b32_e64 v38, 0, v5, s[4:5]
	v_cndmask_b32_e64 v39, 0, v5, s[32:33]
	v_mov_b32_e32 v20, v117
	v_mov_b32_e32 v21, v115
	v_ldexp_f32 v18, v18, v37
	v_ldexp_f32 v37, v36, v38
	v_ldexp_f32 v36, v0, v39
	v_mul_f32_e32 v0, v113, v18
	v_fma_f32 v38, v113, v18, 0
	v_pk_mul_f32 v[18:19], v[20:21], v[36:37]
	v_add_f32_e32 v20, v19, v38
	v_add_f32_e32 v20, v18, v20
	v_div_scale_f32 v21, s[4:5], v20, v20, 1.0
	v_rcp_f32_e32 v37, v21
	v_div_scale_f32 v36, vcc, 1.0, v20, 1.0
	v_fma_f32 v38, -v21, v37, 1.0
	v_fmac_f32_e32 v37, v38, v37
	v_mul_f32_e32 v38, v36, v37
	v_fma_f32 v39, -v21, v38, v36
	v_fmac_f32_e32 v38, v39, v37
	v_fma_f32 v21, -v21, v38, v36
	v_div_fmas_f32 v21, v21, v37, v38
	v_div_fixup_f32 v21, v21, v20, 1.0
	v_mul_f32_e32 v0, v0, v21
	v_mul_f32_e32 v20, v19, v21
	v_mul_f32_e32 v18, v18, v21
	v_lshlrev_b32_e32 v22, 16, v118
	v_and_b32_e32 v23, 0xffff0000, v118
	v_lshlrev_b32_e32 v6, 16, v119
	v_and_b32_e32 v7, 0xffff0000, v119
	v_lshlrev_b32_e32 v30, 16, v120
	v_and_b32_e32 v31, 0xffff0000, v120
	v_lshlrev_b32_e32 v8, 16, v121
	v_and_b32_e32 v9, 0xffff0000, v121
	v_lshlrev_b32_e32 v26, 16, v122
	v_and_b32_e32 v27, 0xffff0000, v122
	v_lshlrev_b32_e32 v10, 16, v123
	v_and_b32_e32 v11, 0xffff0000, v123
	v_lshlrev_b32_e32 v32, 16, v124
	v_and_b32_e32 v33, 0xffff0000, v124
	v_lshlrev_b32_e32 v12, 16, v125
	v_and_b32_e32 v13, 0xffff0000, v125
	v_pk_fma_f32 v[22:23], v[0:1], v[22:23], 0 op_sel_hi:[0,1,0]
	v_pk_fma_f32 v[6:7], v[0:1], v[6:7], 0 op_sel_hi:[0,1,0]
	v_pk_fma_f32 v[30:31], v[0:1], v[30:31], 0 op_sel_hi:[0,1,0]
	v_pk_fma_f32 v[8:9], v[0:1], v[8:9], 0 op_sel_hi:[0,1,0]
	v_lshlrev_b32_e32 v28, 16, v126
	v_and_b32_e32 v29, 0xffff0000, v126
	v_lshlrev_b32_e32 v14, 16, v127
	v_and_b32_e32 v15, 0xffff0000, v127
	v_lshlrev_b32_e32 v34, 16, v128
	v_and_b32_e32 v35, 0xffff0000, v128
	v_lshlrev_b32_e32 v16, 16, v129
	v_and_b32_e32 v17, 0xffff0000, v129
	v_pk_fma_f32 v[22:23], v[20:21], v[26:27], v[22:23] op_sel_hi:[0,1,1]
	v_pk_fma_f32 v[6:7], v[20:21], v[10:11], v[6:7] op_sel_hi:[0,1,1]
	v_pk_fma_f32 v[10:11], v[20:21], v[32:33], v[30:31] op_sel_hi:[0,1,1]
	v_pk_fma_f32 v[8:9], v[20:21], v[12:13], v[8:9] op_sel_hi:[0,1,1]
	v_pk_fma_f32 v[12:13], v[18:19], v[28:29], v[22:23] op_sel_hi:[0,1,1]
	v_pk_fma_f32 v[14:15], v[18:19], v[14:15], v[6:7] op_sel_hi:[0,1,1]
	v_pk_fma_f32 v[10:11], v[18:19], v[34:35], v[10:11] op_sel_hi:[0,1,1]
	v_pk_fma_f32 v[16:17], v[18:19], v[16:17], v[8:9] op_sel_hi:[0,1,1]
	v_cvt_pk_bf16_f32 v118, v12, v13
	v_cvt_pk_bf16_f32 v119, v14, v15
	v_cvt_pk_bf16_f32 v120, v10, v11
	v_cvt_pk_bf16_f32 v121, v16, v17
	global_store_dwordx4 v130, v[118:121], s[10:11]
	s_branch .Lcmb_skip
; __device__ __forceinline__ unsigned pk2(float lo, float hi) { f32x2_t v = {lo, hi}; bf16x2_t b = __builtin_convertvector(v, bf16x2_t); return __builtin_bit_cast(unsigned, b); }
; __device__ __forceinline__ float bflo(unsigned w) { return __uint_as_float(w << 16); }
; __device__ __forceinline__ float bfhi(unsigned w) { return __uint_as_float(w & 0xffff0000u); }
; __device__ __forceinline__ bf16* po_base(unsigned char* ws, int pat) { return (bf16*)(ws + (pat < 2 ? 436 * MiB + (size_t)pat * 32 * MiB : WS_Y)); }
; __device__ __forceinline__ void attn_combine(unsigned char* ws, const float* __restrict__ PM, bf16* CAT, int gtid, int gthreads, int iend = S * 128) {
;     ...
;         for (int p = 0; p < 3; ++p) { const f32x2_t ml = *(const f32x2_t*)(PM + (((size_t)p * S + t) * 8 + hh) * 2); mm[p] = ml[0]; ll[p] = ml[1]; }
;         const float ma = fmaxf(mm[0], fmaxf(mm[1], mm[2]));
;         float w[3], den = 0.f;
; #pragma unroll
;         for (int p = 0; p < 3; ++p) { w[p] = exp2f(mm[p] - ma) * ll[p]; den += w[p]; }
;         const float inv = 1.f / den;
;         float o[8] = {0.f, 0.f, 0.f, 0.f, 0.f, 0.f, 0.f, 0.f};
; #pragma unroll
;         for (int p = 0; p < 3; ++p) {
;             const u32x4 v = *(const u32x4*)(po_base(ws, p) + (size_t)t * 1024 + c); const float wp = w[p] * inv;
;             o[0] += wp * bflo(v.x); o[1] += wp * bfhi(v.x); o[2] += wp * bflo(v.y); o[3] += wp * bfhi(v.y); o[4] += wp * bflo(v.z); o[5] += wp * bfhi(v.z); o[6] += wp * bflo(v.w); o[7] += wp * bfhi(v.w);
;         }
;         u32x4 ov; ov.x = pk2(o[0], o[1]); ov.y = pk2(o[2], o[3]); ov.z = pk2(o[4], o[5]); ov.w = pk2(o[6], o[7]);
;         *(u32x4*)(CAT + (size_t)t * 2048 + c) = ov;
.Lcmb_lastB:
	s_waitcnt vmcnt(18)
	v_max3_f32 v0, v136, v138, v140
	v_sub_f32_e32 v18, v136, v0
	v_sub_f32_e32 v36, v138, v0
	v_sub_f32_e32 v0, v140, v0
	v_cmp_gt_f32_e32 vcc, s19, v18
	v_cmp_gt_f32_e64 s[4:5], s19, v36
	v_cmp_gt_f32_e64 s[32:33], s19, v0
	v_cndmask_b32_e32 v37, 0, v4, vcc
	v_cndmask_b32_e64 v38, 0, v4, s[4:5]
	v_cndmask_b32_e64 v39, 0, v4, s[32:33]
	v_add_f32_e32 v18, v18, v37
	v_add_f32_e32 v36, v36, v38
	v_add_f32_e32 v0, v0, v39
	v_exp_f32_e32 v18, v18
	v_exp_f32_e32 v36, v36
	v_exp_f32_e32 v0, v0
	v_cndmask_b32_e32 v37, 0, v5, vcc
	v_cndmask_b32_e64 v38, 0, v5, s[4:5]
	v_cndmask_b32_e64 v39, 0, v5, s[32:33]
	v_mov_b32_e32 v20, v141
	v_mov_b32_e32 v21, v139
	v_ldexp_f32 v18, v18, v37
	v_ldexp_f32 v37, v36, v38
	v_ldexp_f32 v36, v0, v39
	v_mul_f32_e32 v0, v137, v18
	v_fma_f32 v38, v137, v18, 0
	v_pk_mul_f32 v[18:19], v[20:21], v[36:37]
	v_add_f32_e32 v20, v19, v38
	v_add_f32_e32 v20, v18, v20
	v_div_scale_f32 v21, s[4:5], v20, v20, 1.0
	v_rcp_f32_e32 v37, v21
	v_div_scale_f32 v36, vcc, 1.0, v20, 1.0
	v_fma_f32 v38, -v21, v37, 1.0
	v_fmac_f32_e32 v37, v38, v37
	v_mul_f32_e32 v38, v36, v37
	v_fma_f32 v39, -v21, v38, v36
	v_fmac_f32_e32 v38, v39, v37
	v_fma_f32 v21, -v21, v38, v36
	v_div_fmas_f32 v21, v21, v37, v38
	v_div_fixup_f32 v21, v21, v20, 1.0
	v_mul_f32_e32 v0, v0, v21
	v_mul_f32_e32 v20, v19, v21
	v_mul_f32_e32 v18, v18, v21
	v_lshlrev_b32_e32 v22, 16, v142
	v_and_b32_e32 v23, 0xffff0000, v142
	v_lshlrev_b32_e32 v6, 16, v143
	v_and_b32_e32 v7, 0xffff0000, v143
	v_lshlrev_b32_e32 v30, 16, v144
	v_and_b32_e32 v31, 0xffff0000, v144
	v_lshlrev_b32_e32 v8, 16, v145
	v_and_b32_e32 v9, 0xffff0000, v145
	v_lshlrev_b32_e32 v26, 16, v146
	v_and_b32_e32 v27, 0xffff0000, v146
	v_lshlrev_b32_e32 v10, 16, v147
	v_and_b32_e32 v11, 0xffff0000, v147
	v_lshlrev_b32_e32 v32, 16, v148
	v_and_b32_e32 v33, 0xffff0000, v148
	v_lshlrev_b32_e32 v12, 16, v149
	v_and_b32_e32 v13, 0xffff0000, v149
	v_pk_fma_f32 v[22:23], v[0:1], v[22:23], 0 op_sel_hi:[0,1,0]
	v_pk_fma_f32 v[6:7], v[0:1], v[6:7], 0 op_sel_hi:[0,1,0]
	v_pk_fma_f32 v[30:31], v[0:1], v[30:31], 0 op_sel_hi:[0,1,0]
	v_pk_fma_f32 v[8:9], v[0:1], v[8:9], 0 op_sel_hi:[0,1,0]
	v_lshlrev_b32_e32 v28, 16, v150
	v_and_b32_e32 v29, 0xffff0000, v150
	v_lshlrev_b32_e32 v14, 16, v151
	v_and_b32_e32 v15, 0xffff0000, v151
	v_lshlrev_b32_e32 v34, 16, v152
	v_and_b32_e32 v35, 0xffff0000, v152
	v_lshlrev_b32_e32 v16, 16, v153
	v_and_b32_e32 v17, 0xffff0000, v153
	v_pk_fma_f32 v[22:23], v[20:21], v[26:27], v[22:23] op_sel_hi:[0,1,1]
	v_pk_fma_f32 v[6:7], v[20:21], v[10:11], v[6:7] op_sel_hi:[0,1,1]
	v_pk_fma_f32 v[10:11], v[20:21], v[32:33], v[30:31] op_sel_hi:[0,1,1]
	v_pk_fma_f32 v[8:9], v[20:21], v[12:13], v[8:9] op_sel_hi:[0,1,1]
	v_pk_fma_f32 v[12:13], v[18:19], v[28:29], v[22:23] op_sel_hi:[0,1,1]
	v_pk_fma_f32 v[14:15], v[18:19], v[14:15], v[6:7] op_sel_hi:[0,1,1]
	v_pk_fma_f32 v[10:11], v[18:19], v[34:35], v[10:11] op_sel_hi:[0,1,1]
	v_pk_fma_f32 v[16:17], v[18:19], v[16:17], v[8:9] op_sel_hi:[0,1,1]
	v_cvt_pk_bf16_f32 v142, v12, v13
	v_cvt_pk_bf16_f32 v143, v14, v15
	v_cvt_pk_bf16_f32 v144, v10, v11
	v_cvt_pk_bf16_f32 v145, v16, v17
	global_store_dwordx4 v154, v[142:145], s[10:11]
	s_waitcnt vmcnt(13)
	v_max3_f32 v0, v160, v162, v164
	v_sub_f32_e32 v18, v160, v0
	v_sub_f32_e32 v36, v162, v0
	v_sub_f32_e32 v0, v164, v0
	v_cmp_gt_f32_e32 vcc, s19, v18
	v_cmp_gt_f32_e64 s[4:5], s19, v36
	v_cmp_gt_f32_e64 s[32:33], s19, v0
	v_cndmask_b32_e32 v37, 0, v4, vcc
	v_cndmask_b32_e64 v38, 0, v4, s[4:5]
	v_cndmask_b32_e64 v39, 0, v4, s[32:33]
	v_add_f32_e32 v18, v18, v37
	v_add_f32_e32 v36, v36, v38
	v_add_f32_e32 v0, v0, v39
	v_exp_f32_e32 v18, v18
	v_exp_f32_e32 v36, v36
	v_exp_f32_e32 v0, v0
	v_cndmask_b32_e32 v37, 0, v5, vcc
	v_cndmask_b32_e64 v38, 0, v5, s[4:5]
	v_cndmask_b32_e64 v39, 0, v5, s[32:33]
	v_mov_b32_e32 v20, v165
	v_mov_b32_e32 v21, v163
	v_ldexp_f32 v18, v18, v37
	v_ldexp_f32 v37, v36, v38
	v_ldexp_f32 v36, v0, v39
	v_mul_f32_e32 v0, v161, v18
	v_fma_f32 v38, v161, v18, 0
	v_pk_mul_f32 v[18:19], v[20:21], v[36:37]
	v_add_f32_e32 v20, v19, v38
	v_add_f32_e32 v20, v18, v20
	v_div_scale_f32 v21, s[4:5], v20, v20, 1.0
	v_rcp_f32_e32 v37, v21
	v_div_scale_f32 v36, vcc, 1.0, v20, 1.0
	v_fma_f32 v38, -v21, v37, 1.0
	v_fmac_f32_e32 v37, v38, v37
	v_mul_f32_e32 v38, v36, v37
	v_fma_f32 v39, -v21, v38, v36
	v_fmac_f32_e32 v38, v39, v37
	v_fma_f32 v21, -v21, v38, v36
	v_div_fmas_f32 v21, v21, v37, v38
	v_div_fixup_f32 v21, v21, v20, 1.0
	v_mul_f32_e32 v0, v0, v21
	v_mul_f32_e32 v20, v19, v21
	v_mul_f32_e32 v18, v18, v21
	v_lshlrev_b32_e32 v22, 16, v166
	v_and_b32_e32 v23, 0xffff0000, v166
	v_lshlrev_b32_e32 v6, 16, v167
	v_and_b32_e32 v7, 0xffff0000, v167
	v_lshlrev_b32_e32 v30, 16, v168
	v_and_b32_e32 v31, 0xffff0000, v168
	v_lshlrev_b32_e32 v8, 16, v169
	v_and_b32_e32 v9, 0xffff0000, v169
	v_lshlrev_b32_e32 v26, 16, v170
	v_and_b32_e32 v27, 0xffff0000, v170
	v_lshlrev_b32_e32 v10, 16, v171
	v_and_b32_e32 v11, 0xffff0000, v171
	v_lshlrev_b32_e32 v32, 16, v172
	v_and_b32_e32 v33, 0xffff0000, v172
	v_lshlrev_b32_e32 v12, 16, v173
	v_and_b32_e32 v13, 0xffff0000, v173
	v_pk_fma_f32 v[22:23], v[0:1], v[22:23], 0 op_sel_hi:[0,1,0]
	v_pk_fma_f32 v[6:7], v[0:1], v[6:7], 0 op_sel_hi:[0,1,0]
	v_pk_fma_f32 v[30:31], v[0:1], v[30:31], 0 op_sel_hi:[0,1,0]
	v_pk_fma_f32 v[8:9], v[0:1], v[8:9], 0 op_sel_hi:[0,1,0]
	v_lshlrev_b32_e32 v28, 16, v174
	v_and_b32_e32 v29, 0xffff0000, v174
	v_lshlrev_b32_e32 v14, 16, v175
	v_and_b32_e32 v15, 0xffff0000, v175
	v_lshlrev_b32_e32 v34, 16, v176
	v_and_b32_e32 v35, 0xffff0000, v176
	v_lshlrev_b32_e32 v16, 16, v177
	v_and_b32_e32 v17, 0xffff0000, v177
	v_pk_fma_f32 v[22:23], v[20:21], v[26:27], v[22:23] op_sel_hi:[0,1,1]
	v_pk_fma_f32 v[6:7], v[20:21], v[10:11], v[6:7] op_sel_hi:[0,1,1]
	v_pk_fma_f32 v[10:11], v[20:21], v[32:33], v[30:31] op_sel_hi:[0,1,1]
	v_pk_fma_f32 v[8:9], v[20:21], v[12:13], v[8:9] op_sel_hi:[0,1,1]
	v_pk_fma_f32 v[12:13], v[18:19], v[28:29], v[22:23] op_sel_hi:[0,1,1]
	v_pk_fma_f32 v[14:15], v[18:19], v[14:15], v[6:7] op_sel_hi:[0,1,1]
	v_pk_fma_f32 v[10:11], v[18:19], v[34:35], v[10:11] op_sel_hi:[0,1,1]
	v_pk_fma_f32 v[16:17], v[18:19], v[16:17], v[8:9] op_sel_hi:[0,1,1]
	v_cvt_pk_bf16_f32 v166, v12, v13
	v_cvt_pk_bf16_f32 v167, v14, v15
	v_cvt_pk_bf16_f32 v168, v10, v11
	v_cvt_pk_bf16_f32 v169, v16, v17
	global_store_dwordx4 v178, v[166:169], s[10:11]
	s_waitcnt vmcnt(8)
; __device__ __forceinline__ unsigned pk2(float lo, float hi) { f32x2_t v = {lo, hi}; bf16x2_t b = __builtin_convertvector(v, bf16x2_t); return __builtin_bit_cast(unsigned, b); }
; __device__ __forceinline__ float bflo(unsigned w) { return __uint_as_float(w << 16); }
; __device__ __forceinline__ float bfhi(unsigned w) { return __uint_as_float(w & 0xffff0000u); }
; __device__ __forceinline__ bf16* po_base(unsigned char* ws, int pat) { return (bf16*)(ws + (pat < 2 ? 436 * MiB + (size_t)pat * 32 * MiB : WS_Y)); }
; __device__ __forceinline__ void attn_combine(unsigned char* ws, const float* __restrict__ PM, bf16* CAT, int gtid, int gthreads, int iend = S * 128) {
;     ...
;         for (int p = 0; p < 3; ++p) { const f32x2_t ml = *(const f32x2_t*)(PM + (((size_t)p * S + t) * 8 + hh) * 2); mm[p] = ml[0]; ll[p] = ml[1]; }
;         const float ma = fmaxf(mm[0], fmaxf(mm[1], mm[2]));
;         float w[3], den = 0.f;
; #pragma unroll
;         for (int p = 0; p < 3; ++p) { w[p] = exp2f(mm[p] - ma) * ll[p]; den += w[p]; }
;         const float inv = 1.f / den;
;         float o[8] = {0.f, 0.f, 0.f, 0.f, 0.f, 0.f, 0.f, 0.f};
; #pragma unroll
;         for (int p = 0; p < 3; ++p) {
;             const u32x4 v = *(const u32x4*)(po_base(ws, p) + (size_t)t * 1024 + c); const float wp = w[p] * inv;
;             o[0] += wp * bflo(v.x); o[1] += wp * bfhi(v.x); o[2] += wp * bflo(v.y); o[3] += wp * bfhi(v.y); o[4] += wp * bflo(v.z); o[5] += wp * bfhi(v.z); o[6] += wp * bflo(v.w); o[7] += wp * bfhi(v.w);
;         }
;         u32x4 ov; ov.x = pk2(o[0], o[1]); ov.y = pk2(o[2], o[3]); ov.z = pk2(o[4], o[5]); ov.w = pk2(o[6], o[7]);
;         *(u32x4*)(CAT + (size_t)t * 2048 + c) = ov;
	v_max3_f32 v0, v188, v190, v192
	v_sub_f32_e32 v18, v188, v0
	v_sub_f32_e32 v36, v190, v0
	v_sub_f32_e32 v0, v192, v0
	v_cmp_gt_f32_e32 vcc, s19, v18
	v_cmp_gt_f32_e64 s[4:5], s19, v36
	v_cmp_gt_f32_e64 s[32:33], s19, v0
	v_cndmask_b32_e32 v37, 0, v4, vcc
	v_cndmask_b32_e64 v38, 0, v4, s[4:5]
	v_cndmask_b32_e64 v39, 0, v4, s[32:33]
	v_add_f32_e32 v18, v18, v37
	v_add_f32_e32 v36, v36, v38
	v_add_f32_e32 v0, v0, v39
	v_exp_f32_e32 v18, v18
	v_exp_f32_e32 v36, v36
	v_exp_f32_e32 v0, v0
	v_cndmask_b32_e32 v37, 0, v5, vcc
	v_cndmask_b32_e64 v38, 0, v5, s[4:5]
	v_cndmask_b32_e64 v39, 0, v5, s[32:33]
	v_mov_b32_e32 v20, v193
	v_mov_b32_e32 v21, v191
	v_ldexp_f32 v18, v18, v37
	v_ldexp_f32 v37, v36, v38
	v_ldexp_f32 v36, v0, v39
	v_mul_f32_e32 v0, v189, v18
	v_fma_f32 v38, v189, v18, 0
	v_pk_mul_f32 v[18:19], v[20:21], v[36:37]
	v_add_f32_e32 v20, v19, v38
	v_add_f32_e32 v20, v18, v20
	v_div_scale_f32 v21, s[4:5], v20, v20, 1.0
	v_rcp_f32_e32 v37, v21
	v_div_scale_f32 v36, vcc, 1.0, v20, 1.0
	v_fma_f32 v38, -v21, v37, 1.0
	v_fmac_f32_e32 v37, v38, v37
	v_mul_f32_e32 v38, v36, v37
	v_fma_f32 v39, -v21, v38, v36
	v_fmac_f32_e32 v38, v39, v37
	v_fma_f32 v21, -v21, v38, v36
	v_div_fmas_f32 v21, v21, v37, v38
	v_div_fixup_f32 v21, v21, v20, 1.0
	v_mul_f32_e32 v0, v0, v21
	v_mul_f32_e32 v20, v19, v21
	v_mul_f32_e32 v18, v18, v21
	v_lshlrev_b32_e32 v22, 16, v194
	v_and_b32_e32 v23, 0xffff0000, v194
	v_lshlrev_b32_e32 v6, 16, v195
	v_and_b32_e32 v7, 0xffff0000, v195
	v_lshlrev_b32_e32 v30, 16, v196
	v_and_b32_e32 v31, 0xffff0000, v196
	v_lshlrev_b32_e32 v8, 16, v197
	v_and_b32_e32 v9, 0xffff0000, v197
	v_lshlrev_b32_e32 v26, 16, v198
	v_and_b32_e32 v27, 0xffff0000, v198
	v_lshlrev_b32_e32 v10, 16, v199
	v_and_b32_e32 v11, 0xffff0000, v199
	v_lshlrev_b32_e32 v32, 16, v200
	v_and_b32_e32 v33, 0xffff0000, v200
	v_lshlrev_b32_e32 v12, 16, v201
	v_and_b32_e32 v13, 0xffff0000, v201
	v_pk_fma_f32 v[22:23], v[0:1], v[22:23], 0 op_sel_hi:[0,1,0]
	v_pk_fma_f32 v[6:7], v[0:1], v[6:7], 0 op_sel_hi:[0,1,0]
	v_pk_fma_f32 v[30:31], v[0:1], v[30:31], 0 op_sel_hi:[0,1,0]
	v_pk_fma_f32 v[8:9], v[0:1], v[8:9], 0 op_sel_hi:[0,1,0]
	v_lshlrev_b32_e32 v28, 16, v202
	v_and_b32_e32 v29, 0xffff0000, v202
	v_lshlrev_b32_e32 v14, 16, v203
	v_and_b32_e32 v15, 0xffff0000, v203
	v_lshlrev_b32_e32 v34, 16, v204
	v_and_b32_e32 v35, 0xffff0000, v204
	v_lshlrev_b32_e32 v16, 16, v205
	v_and_b32_e32 v17, 0xffff0000, v205
	v_pk_fma_f32 v[22:23], v[20:21], v[26:27], v[22:23] op_sel_hi:[0,1,1]
	v_pk_fma_f32 v[6:7], v[20:21], v[10:11], v[6:7] op_sel_hi:[0,1,1]
	v_pk_fma_f32 v[10:11], v[20:21], v[32:33], v[30:31] op_sel_hi:[0,1,1]
	v_pk_fma_f32 v[8:9], v[20:21], v[12:13], v[8:9] op_sel_hi:[0,1,1]
	v_pk_fma_f32 v[12:13], v[18:19], v[28:29], v[22:23] op_sel_hi:[0,1,1]
	v_pk_fma_f32 v[14:15], v[18:19], v[14:15], v[6:7] op_sel_hi:[0,1,1]
	v_pk_fma_f32 v[10:11], v[18:19], v[34:35], v[10:11] op_sel_hi:[0,1,1]
	v_pk_fma_f32 v[16:17], v[18:19], v[16:17], v[8:9] op_sel_hi:[0,1,1]
	v_cvt_pk_bf16_f32 v194, v12, v13
	v_cvt_pk_bf16_f32 v195, v14, v15
	v_cvt_pk_bf16_f32 v196, v10, v11
	v_cvt_pk_bf16_f32 v197, v16, v17
	global_store_dwordx4 v206, v[194:197], s[10:11]
	s_waitcnt vmcnt(3)
	v_max3_f32 v0, v212, v214, v216
	v_sub_f32_e32 v18, v212, v0
	v_sub_f32_e32 v36, v214, v0
	v_sub_f32_e32 v0, v216, v0
	v_cmp_gt_f32_e32 vcc, s19, v18
	v_cmp_gt_f32_e64 s[4:5], s19, v36
	v_cmp_gt_f32_e64 s[32:33], s19, v0
	v_cndmask_b32_e32 v37, 0, v4, vcc
	v_cndmask_b32_e64 v38, 0, v4, s[4:5]
	v_cndmask_b32_e64 v39, 0, v4, s[32:33]
	v_add_f32_e32 v18, v18, v37
	v_add_f32_e32 v36, v36, v38
	v_add_f32_e32 v0, v0, v39
	v_exp_f32_e32 v18, v18
	v_exp_f32_e32 v36, v36
	v_exp_f32_e32 v0, v0
	v_cndmask_b32_e32 v37, 0, v5, vcc
	v_cndmask_b32_e64 v38, 0, v5, s[4:5]
	v_cndmask_b32_e64 v39, 0, v5, s[32:33]
	v_mov_b32_e32 v20, v217
	v_mov_b32_e32 v21, v215
	v_ldexp_f32 v18, v18, v37
	v_ldexp_f32 v37, v36, v38
	v_ldexp_f32 v36, v0, v39
	v_mul_f32_e32 v0, v213, v18
	v_fma_f32 v38, v213, v18, 0
	v_pk_mul_f32 v[18:19], v[20:21], v[36:37]
	v_add_f32_e32 v20, v19, v38
	v_add_f32_e32 v20, v18, v20
	v_div_scale_f32 v21, s[4:5], v20, v20, 1.0
	v_rcp_f32_e32 v37, v21
	v_div_scale_f32 v36, vcc, 1.0, v20, 1.0
	v_fma_f32 v38, -v21, v37, 1.0
	v_fmac_f32_e32 v37, v38, v37
	v_mul_f32_e32 v38, v36, v37
	v_fma_f32 v39, -v21, v38, v36
	v_fmac_f32_e32 v38, v39, v37
	v_fma_f32 v21, -v21, v38, v36
	v_div_fmas_f32 v21, v21, v37, v38
	v_div_fixup_f32 v21, v21, v20, 1.0
	v_mul_f32_e32 v0, v0, v21
	v_mul_f32_e32 v20, v19, v21
	v_mul_f32_e32 v18, v18, v21
	v_lshlrev_b32_e32 v22, 16, v218
	v_and_b32_e32 v23, 0xffff0000, v218
	v_lshlrev_b32_e32 v6, 16, v219
	v_and_b32_e32 v7, 0xffff0000, v219
	v_lshlrev_b32_e32 v30, 16, v220
	v_and_b32_e32 v31, 0xffff0000, v220
	v_lshlrev_b32_e32 v8, 16, v221
	v_and_b32_e32 v9, 0xffff0000, v221
	v_lshlrev_b32_e32 v26, 16, v222
	v_and_b32_e32 v27, 0xffff0000, v222
	v_lshlrev_b32_e32 v10, 16, v223
	v_and_b32_e32 v11, 0xffff0000, v223
	v_lshlrev_b32_e32 v32, 16, v224
	v_and_b32_e32 v33, 0xffff0000, v224
	v_lshlrev_b32_e32 v12, 16, v225
	v_and_b32_e32 v13, 0xffff0000, v225
	v_pk_fma_f32 v[22:23], v[0:1], v[22:23], 0 op_sel_hi:[0,1,0]
	v_pk_fma_f32 v[6:7], v[0:1], v[6:7], 0 op_sel_hi:[0,1,0]
	v_pk_fma_f32 v[30:31], v[0:1], v[30:31], 0 op_sel_hi:[0,1,0]
	v_pk_fma_f32 v[8:9], v[0:1], v[8:9], 0 op_sel_hi:[0,1,0]
	v_lshlrev_b32_e32 v28, 16, v226
	v_and_b32_e32 v29, 0xffff0000, v226
	v_lshlrev_b32_e32 v14, 16, v227
	v_and_b32_e32 v15, 0xffff0000, v227
	v_lshlrev_b32_e32 v34, 16, v228
	v_and_b32_e32 v35, 0xffff0000, v228
	v_lshlrev_b32_e32 v16, 16, v229
	v_and_b32_e32 v17, 0xffff0000, v229
	v_pk_fma_f32 v[22:23], v[20:21], v[26:27], v[22:23] op_sel_hi:[0,1,1]
	v_pk_fma_f32 v[6:7], v[20:21], v[10:11], v[6:7] op_sel_hi:[0,1,1]
	v_pk_fma_f32 v[10:11], v[20:21], v[32:33], v[30:31] op_sel_hi:[0,1,1]
	v_pk_fma_f32 v[8:9], v[20:21], v[12:13], v[8:9] op_sel_hi:[0,1,1]
	v_pk_fma_f32 v[12:13], v[18:19], v[28:29], v[22:23] op_sel_hi:[0,1,1]
	v_pk_fma_f32 v[14:15], v[18:19], v[14:15], v[6:7] op_sel_hi:[0,1,1]
	v_pk_fma_f32 v[10:11], v[18:19], v[34:35], v[10:11] op_sel_hi:[0,1,1]
	v_pk_fma_f32 v[16:17], v[18:19], v[16:17], v[8:9] op_sel_hi:[0,1,1]
	v_cvt_pk_bf16_f32 v218, v12, v13
	v_cvt_pk_bf16_f32 v219, v14, v15
	v_cvt_pk_bf16_f32 v220, v10, v11
	v_cvt_pk_bf16_f32 v221, v16, v17
	global_store_dwordx4 v230, v[218:221], s[10:11]
